# speedup vs baseline: 1.0184x; 1.0107x over previous
; __device__ __forceinline__ float row16_sum(float v) { DPP_ADD(v, 0x128); DPP_ADD(v, 0x124); DPP_ADD(v, 0x122); DPP_ADD(v, 0x121); return v; }
; template <int EPI, int N, int K>
; __device__ __forceinline__ void gemm_phase(const bf16_t* __restrict__ A, const bf16_t* __restrict__ Bt, const EpiArgs ea) {
;     ...
;           for (int j = 0; j < 4; ++j) {
;             const int row = brow + ai * 128 + wr * 64 + m * 16 + fq * 4 + j;
;             const u32x2 x2 = *(const u32x2*)(ea.outb + (size_t)row * DM + c0);
;             float4 xn;
;             xn.x = __builtin_bit_cast(float, x2[0] << 16) + acc[ai][0][m][0][j]; xn.y = __builtin_bit_cast(float, x2[0] & 0xffff0000u) + acc[ai][0][m][1][j];
;             xn.z = __builtin_bit_cast(float, x2[1] << 16) + acc[ai][1][m][0][j]; xn.w = __builtin_bit_cast(float, x2[1] & 0xffff0000u) + acc[ai][1][m][1][j];
;             u32x2 o = {pk2(xn.x, xn.y), pk2(xn.z, xn.w)};
;             st_wt(ea.outb + (size_t)row * DM + c0, o);
;             float ss = xn.x * xn.x + xn.y * xn.y + xn.z * xn.z + xn.w * xn.w;
;             ss = row16_sum(ss);
;             if (fr == 0) __hip_atomic_fetch_add(ea.rowsq_out + row, (rsq_t)(ss * RSQ_SCALE), __ATOMIC_RELAXED, __HIP_MEMORY_SCOPE_AGENT);
.LBB0_395:
	v_readlane_b32 s2, v236, 14
	v_readlane_b32 s3, v236, 15
	v_lshrrev_b32_e32 v227, 6, v146
	v_lshlrev_b32_e32 v229, 12, v227
	v_bfe_u32 v227, v146, 2, 2
	v_lshl_add_u32 v229, v227, 7, v229
	v_bfe_u32 v227, v145, 4, 2
	v_lshl_add_u32 v229, v227, 5, v229
	v_lshrrev_b32_e32 v227, 6, v145
	v_lshl_add_u32 v229, v227, 3, v229
	v_add_u32_e32 v229, 0x20410, v229
	v_lshlrev_b32_e32 v238, 16, v162
	v_and_b32_e32 v239, 0xffff0000, v162
	v_lshlrev_b32_e32 v240, 16, v163
	v_and_b32_e32 v241, 0xffff0000, v163
	v_lshlrev_b32_e32 v242, 16, v164
	v_and_b32_e32 v243, 0xffff0000, v164
	v_lshlrev_b32_e32 v244, 16, v165
	v_and_b32_e32 v245, 0xffff0000, v165
	v_lshlrev_b32_e32 v246, 16, v166
	v_and_b32_e32 v247, 0xffff0000, v166
	v_lshlrev_b32_e32 v248, 16, v167
	v_and_b32_e32 v249, 0xffff0000, v167
	v_lshlrev_b32_e32 v250, 16, v168
	v_and_b32_e32 v251, 0xffff0000, v168
	v_lshlrev_b32_e32 v252, 16, v169
	v_and_b32_e32 v253, 0xffff0000, v169
	v_add_f32_e32 v238, v116, v238
	v_add_f32_e32 v239, v112, v239
	v_add_f32_e32 v240, v124, v240
	v_add_f32_e32 v241, v120, v241
	v_add_f32_e32 v242, v117, v242
	v_add_f32_e32 v243, v113, v243
	v_add_f32_e32 v244, v125, v244
	v_add_f32_e32 v245, v121, v245
	v_add_f32_e32 v246, v118, v246
	v_add_f32_e32 v247, v114, v247
	v_add_f32_e32 v248, v126, v248
	v_add_f32_e32 v249, v122, v249
	v_add_f32_e32 v250, v119, v250
	v_add_f32_e32 v251, v115, v251
	v_add_f32_e32 v252, v127, v252
	v_add_f32_e32 v253, v123, v253
	v_cvt_pk_bf16_f32 v132, v238, v239
	v_cvt_pk_bf16_f32 v133, v240, v241
	v_cvt_pk_bf16_f32 v134, v242, v243
	v_cvt_pk_bf16_f32 v135, v244, v245
	v_cvt_pk_bf16_f32 v136, v246, v247
	v_cvt_pk_bf16_f32 v137, v248, v249
	v_cvt_pk_bf16_f32 v156, v250, v251
	v_cvt_pk_bf16_f32 v157, v252, v253
	global_store_dwordx2 v226, v[132:133], s[2:3] sc1
	v_add_u32_e32 v227, 0x1000, v226
	global_store_dwordx2 v227, v[134:135], s[2:3] sc1
	v_add_u32_e32 v228, 0x2000, v226
	global_store_dwordx2 v228, v[136:137], s[2:3] sc1
	v_add_u32_e32 v227, 0x3000, v226
	global_store_dwordx2 v227, v[156:157], s[2:3] sc1
	v_pk_mul_f32 v[238:239], v[238:239], v[238:239]
	v_pk_mul_f32 v[240:241], v[240:241], v[240:241]
	v_pk_mul_f32 v[242:243], v[242:243], v[242:243]
	v_pk_mul_f32 v[244:245], v[244:245], v[244:245]
	v_pk_mul_f32 v[246:247], v[246:247], v[246:247]
	v_pk_mul_f32 v[248:249], v[248:249], v[248:249]
	v_pk_mul_f32 v[250:251], v[250:251], v[250:251]
	v_pk_mul_f32 v[252:253], v[252:253], v[252:253]
	v_add_f32_e32 v158, v238, v239
	v_add_f32_e32 v159, v242, v243
	v_add_f32_e32 v160, v246, v247
	v_add_f32_e32 v161, v250, v251
	v_add_f32_e32 v158, v240, v158
	v_add_f32_e32 v159, v244, v159
	v_add_f32_e32 v160, v248, v160
	v_add_f32_e32 v161, v252, v161
	v_add_f32_e32 v158, v241, v158
	v_add_f32_e32 v159, v245, v159
	v_add_f32_e32 v160, v249, v160
	v_add_f32_e32 v161, v253, v161
	v_add_f32_dpp v158, v158, v158 row_ror:8 row_mask:0xf bank_mask:0xf bound_ctrl:1
	v_add_f32_dpp v159, v159, v159 row_ror:8 row_mask:0xf bank_mask:0xf bound_ctrl:1
	v_add_f32_dpp v160, v160, v160 row_ror:8 row_mask:0xf bank_mask:0xf bound_ctrl:1
	v_add_f32_dpp v161, v161, v161 row_ror:8 row_mask:0xf bank_mask:0xf bound_ctrl:1
	v_add_f32_dpp v158, v158, v158 row_ror:4 row_mask:0xf bank_mask:0xf bound_ctrl:1
	v_add_f32_dpp v159, v159, v159 row_ror:4 row_mask:0xf bank_mask:0xf bound_ctrl:1
	v_add_f32_dpp v160, v160, v160 row_ror:4 row_mask:0xf bank_mask:0xf bound_ctrl:1
	v_add_f32_dpp v161, v161, v161 row_ror:4 row_mask:0xf bank_mask:0xf bound_ctrl:1
	v_add_f32_dpp v158, v158, v158 row_ror:2 row_mask:0xf bank_mask:0xf bound_ctrl:1
	v_add_f32_dpp v159, v159, v159 row_ror:2 row_mask:0xf bank_mask:0xf bound_ctrl:1
	v_add_f32_dpp v160, v160, v160 row_ror:2 row_mask:0xf bank_mask:0xf bound_ctrl:1
	v_add_f32_dpp v161, v161, v161 row_ror:2 row_mask:0xf bank_mask:0xf bound_ctrl:1
	v_add_f32_dpp v158, v158, v158 row_ror:1 row_mask:0xf bank_mask:0xf bound_ctrl:1
	v_add_f32_dpp v159, v159, v159 row_ror:1 row_mask:0xf bank_mask:0xf bound_ctrl:1
	v_add_f32_dpp v160, v160, v160 row_ror:1 row_mask:0xf bank_mask:0xf bound_ctrl:1
	v_add_f32_dpp v161, v161, v161 row_ror:1 row_mask:0xf bank_mask:0xf bound_ctrl:1
	v_mov_b32_e32 v254, v158
	v_mov_b32_dpp v254, v159 quad_perm:[0,1,2,3] row_mask:0xf bank_mask:0x2
	v_mov_b32_dpp v254, v160 quad_perm:[0,1,2,3] row_mask:0xf bank_mask:0x4
	v_mov_b32_dpp v254, v161 quad_perm:[0,1,2,3] row_mask:0xf bank_mask:0x8
	v_mul_f32_e32 v254, 0x49800000, v254
	v_trunc_f32_e32 v254, v254
	v_mul_f32_e32 v255, 0x2f800000, v254
	v_floor_f32_e32 v255, v255
	v_fmac_f32_e32 v254, 0xcf800000, v255
	v_cvt_u32_f32_e32 v116, v254
	v_cvt_u32_f32_e32 v117, v255
	v_lshlrev_b32_e32 v238, 16, v170
	v_and_b32_e32 v239, 0xffff0000, v170
	v_lshlrev_b32_e32 v240, 16, v171
	v_and_b32_e32 v241, 0xffff0000, v171
	v_lshlrev_b32_e32 v242, 16, v172
	v_and_b32_e32 v243, 0xffff0000, v172
	v_lshlrev_b32_e32 v244, 16, v173
	v_and_b32_e32 v245, 0xffff0000, v173
	v_lshlrev_b32_e32 v246, 16, v174
	v_and_b32_e32 v247, 0xffff0000, v174
	v_lshlrev_b32_e32 v248, 16, v175
	v_and_b32_e32 v249, 0xffff0000, v175
	v_lshlrev_b32_e32 v250, 16, v176
	v_and_b32_e32 v251, 0xffff0000, v176
	v_lshlrev_b32_e32 v252, 16, v177
	v_and_b32_e32 v253, 0xffff0000, v177
	v_add_f32_e32 v238, v100, v238
	v_add_f32_e32 v239, v96, v239
	v_add_f32_e32 v240, v108, v240
	v_add_f32_e32 v241, v104, v241
	v_add_f32_e32 v242, v101, v242
	v_add_f32_e32 v243, v97, v243
	v_add_f32_e32 v244, v109, v244
	v_add_f32_e32 v245, v105, v245
	v_add_f32_e32 v246, v102, v246
	v_add_f32_e32 v247, v98, v247
	v_add_f32_e32 v248, v110, v248
	v_add_f32_e32 v249, v106, v249
	v_add_f32_e32 v250, v103, v250
	v_add_f32_e32 v251, v99, v251
; __device__ __forceinline__ float row16_sum(float v) { DPP_ADD(v, 0x128); DPP_ADD(v, 0x124); DPP_ADD(v, 0x122); DPP_ADD(v, 0x121); return v; }
; template <int EPI, int N, int K>
; __device__ __forceinline__ void gemm_phase(const bf16_t* __restrict__ A, const bf16_t* __restrict__ Bt, const EpiArgs ea) {
;     ...
; #pragma unroll
;       for (int ai = 0; ai < 2; ++ai)
; #pragma unroll
;         for (int m = 0; m < 4; ++m)
; #pragma unroll
;           for (int j = 0; j < 4; ++j) {
;             const int row = brow + ai * 128 + wr * 64 + m * 16 + fq * 4 + j;
;             const u32x2 x2 = *(const u32x2*)(ea.outb + (size_t)row * DM + c0);
;             float4 xn;
;             xn.x = __builtin_bit_cast(float, x2[0] << 16) + acc[ai][0][m][0][j]; xn.y = __builtin_bit_cast(float, x2[0] & 0xffff0000u) + acc[ai][0][m][1][j];
;             xn.z = __builtin_bit_cast(float, x2[1] << 16) + acc[ai][1][m][0][j]; xn.w = __builtin_bit_cast(float, x2[1] & 0xffff0000u) + acc[ai][1][m][1][j];
;             u32x2 o = {pk2(xn.x, xn.y), pk2(xn.z, xn.w)};
;             st_wt(ea.outb + (size_t)row * DM + c0, o);
;             float ss = xn.x * xn.x + xn.y * xn.y + xn.z * xn.z + xn.w * xn.w;
;             ss = row16_sum(ss);
;             if (fr == 0) __hip_atomic_fetch_add(ea.rowsq_out + row, (rsq_t)(ss * RSQ_SCALE), __ATOMIC_RELAXED, __HIP_MEMORY_SCOPE_AGENT);
;           }
	v_add_f32_e32 v252, v111, v252
	v_add_f32_e32 v253, v107, v253
	v_cvt_pk_bf16_f32 v132, v238, v239
	v_cvt_pk_bf16_f32 v133, v240, v241
	v_cvt_pk_bf16_f32 v134, v242, v243
	v_cvt_pk_bf16_f32 v135, v244, v245
	v_cvt_pk_bf16_f32 v136, v246, v247
	v_cvt_pk_bf16_f32 v137, v248, v249
	v_cvt_pk_bf16_f32 v156, v250, v251
	v_cvt_pk_bf16_f32 v157, v252, v253
	v_add_u32_e32 v228, 0x10000, v226
	global_store_dwordx2 v228, v[132:133], s[2:3] sc1
	v_add_u32_e32 v227, 0x11000, v226
	global_store_dwordx2 v227, v[134:135], s[2:3] sc1
	v_add_u32_e32 v228, 0x12000, v226
	global_store_dwordx2 v228, v[136:137], s[2:3] sc1
	v_add_u32_e32 v227, 0x13000, v226
	global_store_dwordx2 v227, v[156:157], s[2:3] sc1
	v_pk_mul_f32 v[238:239], v[238:239], v[238:239]
	v_pk_mul_f32 v[240:241], v[240:241], v[240:241]
	v_pk_mul_f32 v[242:243], v[242:243], v[242:243]
	v_pk_mul_f32 v[244:245], v[244:245], v[244:245]
	v_pk_mul_f32 v[246:247], v[246:247], v[246:247]
	v_pk_mul_f32 v[248:249], v[248:249], v[248:249]
	v_pk_mul_f32 v[250:251], v[250:251], v[250:251]
	v_pk_mul_f32 v[252:253], v[252:253], v[252:253]
	v_add_f32_e32 v158, v238, v239
	v_add_f32_e32 v159, v242, v243
	v_add_f32_e32 v160, v246, v247
	v_add_f32_e32 v161, v250, v251
	v_add_f32_e32 v158, v240, v158
	v_add_f32_e32 v159, v244, v159
	v_add_f32_e32 v160, v248, v160
	v_add_f32_e32 v161, v252, v161
	v_add_f32_e32 v158, v241, v158
	v_add_f32_e32 v159, v245, v159
	v_add_f32_e32 v160, v249, v160
	v_add_f32_e32 v161, v253, v161
	v_add_f32_dpp v158, v158, v158 row_ror:8 row_mask:0xf bank_mask:0xf bound_ctrl:1
	v_add_f32_dpp v159, v159, v159 row_ror:8 row_mask:0xf bank_mask:0xf bound_ctrl:1
	v_add_f32_dpp v160, v160, v160 row_ror:8 row_mask:0xf bank_mask:0xf bound_ctrl:1
	v_add_f32_dpp v161, v161, v161 row_ror:8 row_mask:0xf bank_mask:0xf bound_ctrl:1
	v_add_f32_dpp v158, v158, v158 row_ror:4 row_mask:0xf bank_mask:0xf bound_ctrl:1
	v_add_f32_dpp v159, v159, v159 row_ror:4 row_mask:0xf bank_mask:0xf bound_ctrl:1
	v_add_f32_dpp v160, v160, v160 row_ror:4 row_mask:0xf bank_mask:0xf bound_ctrl:1
	v_add_f32_dpp v161, v161, v161 row_ror:4 row_mask:0xf bank_mask:0xf bound_ctrl:1
	v_add_f32_dpp v158, v158, v158 row_ror:2 row_mask:0xf bank_mask:0xf bound_ctrl:1
	v_add_f32_dpp v159, v159, v159 row_ror:2 row_mask:0xf bank_mask:0xf bound_ctrl:1
	v_add_f32_dpp v160, v160, v160 row_ror:2 row_mask:0xf bank_mask:0xf bound_ctrl:1
	v_add_f32_dpp v161, v161, v161 row_ror:2 row_mask:0xf bank_mask:0xf bound_ctrl:1
	v_add_f32_dpp v158, v158, v158 row_ror:1 row_mask:0xf bank_mask:0xf bound_ctrl:1
	v_add_f32_dpp v159, v159, v159 row_ror:1 row_mask:0xf bank_mask:0xf bound_ctrl:1
	v_add_f32_dpp v160, v160, v160 row_ror:1 row_mask:0xf bank_mask:0xf bound_ctrl:1
	v_add_f32_dpp v161, v161, v161 row_ror:1 row_mask:0xf bank_mask:0xf bound_ctrl:1
	v_mov_b32_e32 v254, v158
	v_mov_b32_dpp v254, v159 quad_perm:[0,1,2,3] row_mask:0xf bank_mask:0x2
	v_mov_b32_dpp v254, v160 quad_perm:[0,1,2,3] row_mask:0xf bank_mask:0x4
	v_mov_b32_dpp v254, v161 quad_perm:[0,1,2,3] row_mask:0xf bank_mask:0x8
	v_mul_f32_e32 v254, 0x49800000, v254
	v_trunc_f32_e32 v254, v254
	v_mul_f32_e32 v255, 0x2f800000, v254
	v_floor_f32_e32 v255, v255
	v_fmac_f32_e32 v254, 0xcf800000, v255
	v_cvt_u32_f32_e32 v100, v254
	v_cvt_u32_f32_e32 v101, v255
	v_lshlrev_b32_e32 v238, 16, v178
	v_and_b32_e32 v239, 0xffff0000, v178
	v_lshlrev_b32_e32 v240, 16, v179
	v_and_b32_e32 v241, 0xffff0000, v179
	v_lshlrev_b32_e32 v242, 16, v180
	v_and_b32_e32 v243, 0xffff0000, v180
	v_lshlrev_b32_e32 v244, 16, v181
	v_and_b32_e32 v245, 0xffff0000, v181
	v_lshlrev_b32_e32 v246, 16, v182
	v_and_b32_e32 v247, 0xffff0000, v182
	v_lshlrev_b32_e32 v248, 16, v183
	v_and_b32_e32 v249, 0xffff0000, v183
	v_lshlrev_b32_e32 v250, 16, v184
	v_and_b32_e32 v251, 0xffff0000, v184
	v_lshlrev_b32_e32 v252, 16, v185
	v_and_b32_e32 v253, 0xffff0000, v185
	v_add_f32_e32 v238, v84, v238
	v_add_f32_e32 v239, v80, v239
	v_add_f32_e32 v240, v92, v240
	v_add_f32_e32 v241, v88, v241
	v_add_f32_e32 v242, v85, v242
	v_add_f32_e32 v243, v81, v243
	v_add_f32_e32 v244, v93, v244
	v_add_f32_e32 v245, v89, v245
	v_add_f32_e32 v246, v86, v246
	v_add_f32_e32 v247, v82, v247
	v_add_f32_e32 v248, v94, v248
	v_add_f32_e32 v249, v90, v249
	v_add_f32_e32 v250, v87, v250
	v_add_f32_e32 v251, v83, v251
	v_add_f32_e32 v252, v95, v252
	v_add_f32_e32 v253, v91, v253
	v_cvt_pk_bf16_f32 v132, v238, v239
	v_cvt_pk_bf16_f32 v133, v240, v241
	v_cvt_pk_bf16_f32 v134, v242, v243
	v_cvt_pk_bf16_f32 v135, v244, v245
	v_cvt_pk_bf16_f32 v136, v246, v247
	v_cvt_pk_bf16_f32 v137, v248, v249
	v_cvt_pk_bf16_f32 v156, v250, v251
	v_cvt_pk_bf16_f32 v157, v252, v253
	v_add_u32_e32 v228, 0x20000, v226
	global_store_dwordx2 v228, v[132:133], s[2:3] sc1
	v_add_u32_e32 v227, 0x21000, v226
	global_store_dwordx2 v227, v[134:135], s[2:3] sc1
	v_add_u32_e32 v228, 0x22000, v226
	global_store_dwordx2 v228, v[136:137], s[2:3] sc1
	v_add_u32_e32 v227, 0x23000, v226
	global_store_dwordx2 v227, v[156:157], s[2:3] sc1
	v_pk_mul_f32 v[238:239], v[238:239], v[238:239]
	v_pk_mul_f32 v[240:241], v[240:241], v[240:241]
	v_pk_mul_f32 v[242:243], v[242:243], v[242:243]
	v_pk_mul_f32 v[244:245], v[244:245], v[244:245]
	v_pk_mul_f32 v[246:247], v[246:247], v[246:247]
	v_pk_mul_f32 v[248:249], v[248:249], v[248:249]
	v_pk_mul_f32 v[250:251], v[250:251], v[250:251]
	v_pk_mul_f32 v[252:253], v[252:253], v[252:253]
	v_add_f32_e32 v158, v238, v239
	v_add_f32_e32 v159, v242, v243
	v_add_f32_e32 v160, v246, v247
	v_add_f32_e32 v161, v250, v251
	v_add_f32_e32 v158, v240, v158
	v_add_f32_e32 v159, v244, v159
	v_add_f32_e32 v160, v248, v160
	v_add_f32_e32 v161, v252, v161
	v_add_f32_e32 v158, v241, v158
; __device__ __forceinline__ float row16_sum(float v) { DPP_ADD(v, 0x128); DPP_ADD(v, 0x124); DPP_ADD(v, 0x122); DPP_ADD(v, 0x121); return v; }
; template <int EPI, int N, int K>
; __device__ __forceinline__ void gemm_phase(const bf16_t* __restrict__ A, const bf16_t* __restrict__ Bt, const EpiArgs ea) {
;     ...
; #pragma unroll
;       for (int ai = 0; ai < 2; ++ai)
; #pragma unroll
;         for (int m = 0; m < 4; ++m)
; #pragma unroll
;           for (int j = 0; j < 4; ++j) {
;             const int row = brow + ai * 128 + wr * 64 + m * 16 + fq * 4 + j;
;             const u32x2 x2 = *(const u32x2*)(ea.outb + (size_t)row * DM + c0);
;             float4 xn;
;             xn.x = __builtin_bit_cast(float, x2[0] << 16) + acc[ai][0][m][0][j]; xn.y = __builtin_bit_cast(float, x2[0] & 0xffff0000u) + acc[ai][0][m][1][j];
;             xn.z = __builtin_bit_cast(float, x2[1] << 16) + acc[ai][1][m][0][j]; xn.w = __builtin_bit_cast(float, x2[1] & 0xffff0000u) + acc[ai][1][m][1][j];
;             u32x2 o = {pk2(xn.x, xn.y), pk2(xn.z, xn.w)};
;             st_wt(ea.outb + (size_t)row * DM + c0, o);
;             float ss = xn.x * xn.x + xn.y * xn.y + xn.z * xn.z + xn.w * xn.w;
;             ss = row16_sum(ss);
;             if (fr == 0) __hip_atomic_fetch_add(ea.rowsq_out + row, (rsq_t)(ss * RSQ_SCALE), __ATOMIC_RELAXED, __HIP_MEMORY_SCOPE_AGENT);
;           }
	v_add_f32_e32 v159, v245, v159
	v_add_f32_e32 v160, v249, v160
	v_add_f32_e32 v161, v253, v161
	v_add_f32_dpp v158, v158, v158 row_ror:8 row_mask:0xf bank_mask:0xf bound_ctrl:1
	v_add_f32_dpp v159, v159, v159 row_ror:8 row_mask:0xf bank_mask:0xf bound_ctrl:1
	v_add_f32_dpp v160, v160, v160 row_ror:8 row_mask:0xf bank_mask:0xf bound_ctrl:1
	v_add_f32_dpp v161, v161, v161 row_ror:8 row_mask:0xf bank_mask:0xf bound_ctrl:1
	v_add_f32_dpp v158, v158, v158 row_ror:4 row_mask:0xf bank_mask:0xf bound_ctrl:1
	v_add_f32_dpp v159, v159, v159 row_ror:4 row_mask:0xf bank_mask:0xf bound_ctrl:1
	v_add_f32_dpp v160, v160, v160 row_ror:4 row_mask:0xf bank_mask:0xf bound_ctrl:1
	v_add_f32_dpp v161, v161, v161 row_ror:4 row_mask:0xf bank_mask:0xf bound_ctrl:1
	v_add_f32_dpp v158, v158, v158 row_ror:2 row_mask:0xf bank_mask:0xf bound_ctrl:1
	v_add_f32_dpp v159, v159, v159 row_ror:2 row_mask:0xf bank_mask:0xf bound_ctrl:1
	v_add_f32_dpp v160, v160, v160 row_ror:2 row_mask:0xf bank_mask:0xf bound_ctrl:1
	v_add_f32_dpp v161, v161, v161 row_ror:2 row_mask:0xf bank_mask:0xf bound_ctrl:1
	v_add_f32_dpp v158, v158, v158 row_ror:1 row_mask:0xf bank_mask:0xf bound_ctrl:1
	v_add_f32_dpp v159, v159, v159 row_ror:1 row_mask:0xf bank_mask:0xf bound_ctrl:1
	v_add_f32_dpp v160, v160, v160 row_ror:1 row_mask:0xf bank_mask:0xf bound_ctrl:1
	v_add_f32_dpp v161, v161, v161 row_ror:1 row_mask:0xf bank_mask:0xf bound_ctrl:1
	v_mov_b32_e32 v254, v158
	v_mov_b32_dpp v254, v159 quad_perm:[0,1,2,3] row_mask:0xf bank_mask:0x2
	v_mov_b32_dpp v254, v160 quad_perm:[0,1,2,3] row_mask:0xf bank_mask:0x4
	v_mov_b32_dpp v254, v161 quad_perm:[0,1,2,3] row_mask:0xf bank_mask:0x8
	v_mul_f32_e32 v254, 0x49800000, v254
	v_trunc_f32_e32 v254, v254
	v_mul_f32_e32 v255, 0x2f800000, v254
	v_floor_f32_e32 v255, v255
	v_fmac_f32_e32 v254, 0xcf800000, v255
	v_cvt_u32_f32_e32 v84, v254
	v_cvt_u32_f32_e32 v85, v255
	v_lshlrev_b32_e32 v238, 16, v186
	v_and_b32_e32 v239, 0xffff0000, v186
	v_lshlrev_b32_e32 v240, 16, v187
	v_and_b32_e32 v241, 0xffff0000, v187
	v_lshlrev_b32_e32 v242, 16, v188
	v_and_b32_e32 v243, 0xffff0000, v188
	v_lshlrev_b32_e32 v244, 16, v189
	v_and_b32_e32 v245, 0xffff0000, v189
	v_lshlrev_b32_e32 v246, 16, v190
	v_and_b32_e32 v247, 0xffff0000, v190
	v_lshlrev_b32_e32 v248, 16, v191
	v_and_b32_e32 v249, 0xffff0000, v191
	v_lshlrev_b32_e32 v250, 16, v192
	v_and_b32_e32 v251, 0xffff0000, v192
	v_lshlrev_b32_e32 v252, 16, v193
	v_and_b32_e32 v253, 0xffff0000, v193
	v_add_f32_e32 v238, v68, v238
	v_add_f32_e32 v239, v64, v239
	v_add_f32_e32 v240, v76, v240
	v_add_f32_e32 v241, v72, v241
	v_add_f32_e32 v242, v69, v242
	v_add_f32_e32 v243, v65, v243
	v_add_f32_e32 v244, v77, v244
	v_add_f32_e32 v245, v73, v245
	v_add_f32_e32 v246, v70, v246
	v_add_f32_e32 v247, v66, v247
	v_add_f32_e32 v248, v78, v248
	v_add_f32_e32 v249, v74, v249
	v_add_f32_e32 v250, v71, v250
	v_add_f32_e32 v251, v67, v251
	v_add_f32_e32 v252, v79, v252
	v_add_f32_e32 v253, v75, v253
	v_cvt_pk_bf16_f32 v132, v238, v239
	v_cvt_pk_bf16_f32 v133, v240, v241
	v_cvt_pk_bf16_f32 v134, v242, v243
	v_cvt_pk_bf16_f32 v135, v244, v245
	v_cvt_pk_bf16_f32 v136, v246, v247
	v_cvt_pk_bf16_f32 v137, v248, v249
	v_cvt_pk_bf16_f32 v156, v250, v251
	v_cvt_pk_bf16_f32 v157, v252, v253
	v_add_u32_e32 v228, 0x30000, v226
	global_store_dwordx2 v228, v[132:133], s[2:3] sc1
	v_add_u32_e32 v227, 0x31000, v226
	global_store_dwordx2 v227, v[134:135], s[2:3] sc1
	v_add_u32_e32 v228, 0x32000, v226
	global_store_dwordx2 v228, v[136:137], s[2:3] sc1
	v_add_u32_e32 v227, 0x33000, v226
	global_store_dwordx2 v227, v[156:157], s[2:3] sc1
	v_pk_mul_f32 v[238:239], v[238:239], v[238:239]
	v_pk_mul_f32 v[240:241], v[240:241], v[240:241]
	v_pk_mul_f32 v[242:243], v[242:243], v[242:243]
	v_pk_mul_f32 v[244:245], v[244:245], v[244:245]
	v_pk_mul_f32 v[246:247], v[246:247], v[246:247]
	v_pk_mul_f32 v[248:249], v[248:249], v[248:249]
	v_pk_mul_f32 v[250:251], v[250:251], v[250:251]
	v_pk_mul_f32 v[252:253], v[252:253], v[252:253]
	v_add_f32_e32 v158, v238, v239
	v_add_f32_e32 v159, v242, v243
	v_add_f32_e32 v160, v246, v247
	v_add_f32_e32 v161, v250, v251
	v_add_f32_e32 v158, v240, v158
	v_add_f32_e32 v159, v244, v159
	v_add_f32_e32 v160, v248, v160
	v_add_f32_e32 v161, v252, v161
	v_add_f32_e32 v158, v241, v158
	v_add_f32_e32 v159, v245, v159
	v_add_f32_e32 v160, v249, v160
	v_add_f32_e32 v161, v253, v161
	v_add_f32_dpp v158, v158, v158 row_ror:8 row_mask:0xf bank_mask:0xf bound_ctrl:1
	v_add_f32_dpp v159, v159, v159 row_ror:8 row_mask:0xf bank_mask:0xf bound_ctrl:1
	v_add_f32_dpp v160, v160, v160 row_ror:8 row_mask:0xf bank_mask:0xf bound_ctrl:1
	v_add_f32_dpp v161, v161, v161 row_ror:8 row_mask:0xf bank_mask:0xf bound_ctrl:1
	v_add_f32_dpp v158, v158, v158 row_ror:4 row_mask:0xf bank_mask:0xf bound_ctrl:1
	v_add_f32_dpp v159, v159, v159 row_ror:4 row_mask:0xf bank_mask:0xf bound_ctrl:1
	v_add_f32_dpp v160, v160, v160 row_ror:4 row_mask:0xf bank_mask:0xf bound_ctrl:1
	v_add_f32_dpp v161, v161, v161 row_ror:4 row_mask:0xf bank_mask:0xf bound_ctrl:1
	v_add_f32_dpp v158, v158, v158 row_ror:2 row_mask:0xf bank_mask:0xf bound_ctrl:1
	v_add_f32_dpp v159, v159, v159 row_ror:2 row_mask:0xf bank_mask:0xf bound_ctrl:1
	v_add_f32_dpp v160, v160, v160 row_ror:2 row_mask:0xf bank_mask:0xf bound_ctrl:1
	v_add_f32_dpp v161, v161, v161 row_ror:2 row_mask:0xf bank_mask:0xf bound_ctrl:1
	v_add_f32_dpp v158, v158, v158 row_ror:1 row_mask:0xf bank_mask:0xf bound_ctrl:1
	v_add_f32_dpp v159, v159, v159 row_ror:1 row_mask:0xf bank_mask:0xf bound_ctrl:1
	v_add_f32_dpp v160, v160, v160 row_ror:1 row_mask:0xf bank_mask:0xf bound_ctrl:1
	v_add_f32_dpp v161, v161, v161 row_ror:1 row_mask:0xf bank_mask:0xf bound_ctrl:1
; __device__ __forceinline__ float row16_sum(float v) { DPP_ADD(v, 0x128); DPP_ADD(v, 0x124); DPP_ADD(v, 0x122); DPP_ADD(v, 0x121); return v; }
; template <int EPI, int N, int K>
; __device__ __forceinline__ void gemm_phase(const bf16_t* __restrict__ A, const bf16_t* __restrict__ Bt, const EpiArgs ea) {
;     ...
; #pragma unroll
;       for (int ai = 0; ai < 2; ++ai)
; #pragma unroll
;         for (int m = 0; m < 4; ++m)
; #pragma unroll
;           for (int j = 0; j < 4; ++j) {
;             const int row = brow + ai * 128 + wr * 64 + m * 16 + fq * 4 + j;
;             const u32x2 x2 = *(const u32x2*)(ea.outb + (size_t)row * DM + c0);
;             float4 xn;
;             xn.x = __builtin_bit_cast(float, x2[0] << 16) + acc[ai][0][m][0][j]; xn.y = __builtin_bit_cast(float, x2[0] & 0xffff0000u) + acc[ai][0][m][1][j];
;             xn.z = __builtin_bit_cast(float, x2[1] << 16) + acc[ai][1][m][0][j]; xn.w = __builtin_bit_cast(float, x2[1] & 0xffff0000u) + acc[ai][1][m][1][j];
;             u32x2 o = {pk2(xn.x, xn.y), pk2(xn.z, xn.w)};
;             st_wt(ea.outb + (size_t)row * DM + c0, o);
;             float ss = xn.x * xn.x + xn.y * xn.y + xn.z * xn.z + xn.w * xn.w;
;             ss = row16_sum(ss);
;             if (fr == 0) __hip_atomic_fetch_add(ea.rowsq_out + row, (rsq_t)(ss * RSQ_SCALE), __ATOMIC_RELAXED, __HIP_MEMORY_SCOPE_AGENT);
;           }
	v_mov_b32_e32 v254, v158
	v_mov_b32_dpp v254, v159 quad_perm:[0,1,2,3] row_mask:0xf bank_mask:0x2
	v_mov_b32_dpp v254, v160 quad_perm:[0,1,2,3] row_mask:0xf bank_mask:0x4
	v_mov_b32_dpp v254, v161 quad_perm:[0,1,2,3] row_mask:0xf bank_mask:0x8
	v_mul_f32_e32 v254, 0x49800000, v254
	v_trunc_f32_e32 v254, v254
	v_mul_f32_e32 v255, 0x2f800000, v254
	v_floor_f32_e32 v255, v255
	v_fmac_f32_e32 v254, 0xcf800000, v255
	v_cvt_u32_f32_e32 v68, v254
	v_cvt_u32_f32_e32 v69, v255
	v_lshlrev_b32_e32 v238, 16, v194
	v_and_b32_e32 v239, 0xffff0000, v194
	v_lshlrev_b32_e32 v240, 16, v195
	v_and_b32_e32 v241, 0xffff0000, v195
	v_lshlrev_b32_e32 v242, 16, v196
	v_and_b32_e32 v243, 0xffff0000, v196
	v_lshlrev_b32_e32 v244, 16, v197
	v_and_b32_e32 v245, 0xffff0000, v197
	v_lshlrev_b32_e32 v246, 16, v198
	v_and_b32_e32 v247, 0xffff0000, v198
	v_lshlrev_b32_e32 v248, 16, v199
	v_and_b32_e32 v249, 0xffff0000, v199
	v_lshlrev_b32_e32 v250, 16, v200
	v_and_b32_e32 v251, 0xffff0000, v200
	v_lshlrev_b32_e32 v252, 16, v201
	v_and_b32_e32 v253, 0xffff0000, v201
	v_add_f32_e32 v238, v52, v238
	v_add_f32_e32 v239, v48, v239
	v_add_f32_e32 v240, v60, v240
	v_add_f32_e32 v241, v56, v241
	v_add_f32_e32 v242, v53, v242
	v_add_f32_e32 v243, v49, v243
	v_add_f32_e32 v244, v61, v244
	v_add_f32_e32 v245, v57, v245
	v_add_f32_e32 v246, v54, v246
	v_add_f32_e32 v247, v50, v247
	v_add_f32_e32 v248, v62, v248
	v_add_f32_e32 v249, v58, v249
	v_add_f32_e32 v250, v55, v250
	v_add_f32_e32 v251, v51, v251
	v_add_f32_e32 v252, v63, v252
	v_add_f32_e32 v253, v59, v253
	v_cvt_pk_bf16_f32 v132, v238, v239
	v_cvt_pk_bf16_f32 v133, v240, v241
	v_cvt_pk_bf16_f32 v134, v242, v243
	v_cvt_pk_bf16_f32 v135, v244, v245
	v_cvt_pk_bf16_f32 v136, v246, v247
	v_cvt_pk_bf16_f32 v137, v248, v249
	v_cvt_pk_bf16_f32 v156, v250, v251
	v_cvt_pk_bf16_f32 v157, v252, v253
	v_add_u32_e32 v228, 0x80000, v226
	global_store_dwordx2 v228, v[132:133], s[2:3] sc1
	v_add_u32_e32 v227, 0x81000, v226
	global_store_dwordx2 v227, v[134:135], s[2:3] sc1
	v_add_u32_e32 v228, 0x82000, v226
	global_store_dwordx2 v228, v[136:137], s[2:3] sc1
	v_add_u32_e32 v227, 0x83000, v226
	global_store_dwordx2 v227, v[156:157], s[2:3] sc1
	v_pk_mul_f32 v[238:239], v[238:239], v[238:239]
	v_pk_mul_f32 v[240:241], v[240:241], v[240:241]
	v_pk_mul_f32 v[242:243], v[242:243], v[242:243]
	v_pk_mul_f32 v[244:245], v[244:245], v[244:245]
	v_pk_mul_f32 v[246:247], v[246:247], v[246:247]
	v_pk_mul_f32 v[248:249], v[248:249], v[248:249]
	v_pk_mul_f32 v[250:251], v[250:251], v[250:251]
	v_pk_mul_f32 v[252:253], v[252:253], v[252:253]
	v_add_f32_e32 v158, v238, v239
	v_add_f32_e32 v159, v242, v243
	v_add_f32_e32 v160, v246, v247
	v_add_f32_e32 v161, v250, v251
	v_add_f32_e32 v158, v240, v158
	v_add_f32_e32 v159, v244, v159
	v_add_f32_e32 v160, v248, v160
	v_add_f32_e32 v161, v252, v161
	v_add_f32_e32 v158, v241, v158
	v_add_f32_e32 v159, v245, v159
	v_add_f32_e32 v160, v249, v160
	v_add_f32_e32 v161, v253, v161
	v_add_f32_dpp v158, v158, v158 row_ror:8 row_mask:0xf bank_mask:0xf bound_ctrl:1
	v_add_f32_dpp v159, v159, v159 row_ror:8 row_mask:0xf bank_mask:0xf bound_ctrl:1
	v_add_f32_dpp v160, v160, v160 row_ror:8 row_mask:0xf bank_mask:0xf bound_ctrl:1
	v_add_f32_dpp v161, v161, v161 row_ror:8 row_mask:0xf bank_mask:0xf bound_ctrl:1
	v_add_f32_dpp v158, v158, v158 row_ror:4 row_mask:0xf bank_mask:0xf bound_ctrl:1
	v_add_f32_dpp v159, v159, v159 row_ror:4 row_mask:0xf bank_mask:0xf bound_ctrl:1
	v_add_f32_dpp v160, v160, v160 row_ror:4 row_mask:0xf bank_mask:0xf bound_ctrl:1
	v_add_f32_dpp v161, v161, v161 row_ror:4 row_mask:0xf bank_mask:0xf bound_ctrl:1
	v_add_f32_dpp v158, v158, v158 row_ror:2 row_mask:0xf bank_mask:0xf bound_ctrl:1
	v_add_f32_dpp v159, v159, v159 row_ror:2 row_mask:0xf bank_mask:0xf bound_ctrl:1
	v_add_f32_dpp v160, v160, v160 row_ror:2 row_mask:0xf bank_mask:0xf bound_ctrl:1
	v_add_f32_dpp v161, v161, v161 row_ror:2 row_mask:0xf bank_mask:0xf bound_ctrl:1
	v_add_f32_dpp v158, v158, v158 row_ror:1 row_mask:0xf bank_mask:0xf bound_ctrl:1
	v_add_f32_dpp v159, v159, v159 row_ror:1 row_mask:0xf bank_mask:0xf bound_ctrl:1
	v_add_f32_dpp v160, v160, v160 row_ror:1 row_mask:0xf bank_mask:0xf bound_ctrl:1
	v_add_f32_dpp v161, v161, v161 row_ror:1 row_mask:0xf bank_mask:0xf bound_ctrl:1
	v_mov_b32_e32 v254, v158
	v_mov_b32_dpp v254, v159 quad_perm:[0,1,2,3] row_mask:0xf bank_mask:0x2
	v_mov_b32_dpp v254, v160 quad_perm:[0,1,2,3] row_mask:0xf bank_mask:0x4
	v_mov_b32_dpp v254, v161 quad_perm:[0,1,2,3] row_mask:0xf bank_mask:0x8
	v_mul_f32_e32 v254, 0x49800000, v254
	v_trunc_f32_e32 v254, v254
	v_mul_f32_e32 v255, 0x2f800000, v254
	v_floor_f32_e32 v255, v255
	v_fmac_f32_e32 v254, 0xcf800000, v255
	v_cvt_u32_f32_e32 v52, v254
	v_cvt_u32_f32_e32 v53, v255
	v_lshlrev_b32_e32 v238, 16, v202
	v_and_b32_e32 v239, 0xffff0000, v202
	v_lshlrev_b32_e32 v240, 16, v203
	v_and_b32_e32 v241, 0xffff0000, v203
	v_lshlrev_b32_e32 v242, 16, v204
	v_and_b32_e32 v243, 0xffff0000, v204
	v_lshlrev_b32_e32 v244, 16, v205
	v_and_b32_e32 v245, 0xffff0000, v205
	v_lshlrev_b32_e32 v246, 16, v206
	v_and_b32_e32 v247, 0xffff0000, v206
	v_lshlrev_b32_e32 v248, 16, v207
	v_and_b32_e32 v249, 0xffff0000, v207
	v_lshlrev_b32_e32 v250, 16, v208
	v_and_b32_e32 v251, 0xffff0000, v208
	v_lshlrev_b32_e32 v252, 16, v209
	v_and_b32_e32 v253, 0xffff0000, v209
	v_add_f32_e32 v238, v36, v238
	v_add_f32_e32 v239, v32, v239
	v_add_f32_e32 v240, v44, v240
	v_add_f32_e32 v241, v40, v241
	v_add_f32_e32 v242, v37, v242
	v_add_f32_e32 v243, v33, v243
	v_add_f32_e32 v244, v45, v244
	v_add_f32_e32 v245, v41, v245
	v_add_f32_e32 v246, v38, v246
	v_add_f32_e32 v247, v34, v247
; __device__ __forceinline__ float row16_sum(float v) { DPP_ADD(v, 0x128); DPP_ADD(v, 0x124); DPP_ADD(v, 0x122); DPP_ADD(v, 0x121); return v; }
; template <int EPI, int N, int K>
; __device__ __forceinline__ void gemm_phase(const bf16_t* __restrict__ A, const bf16_t* __restrict__ Bt, const EpiArgs ea) {
;     ...
; #pragma unroll
;       for (int ai = 0; ai < 2; ++ai)
; #pragma unroll
;         for (int m = 0; m < 4; ++m)
; #pragma unroll
;           for (int j = 0; j < 4; ++j) {
;             const int row = brow + ai * 128 + wr * 64 + m * 16 + fq * 4 + j;
;             const u32x2 x2 = *(const u32x2*)(ea.outb + (size_t)row * DM + c0);
;             float4 xn;
;             xn.x = __builtin_bit_cast(float, x2[0] << 16) + acc[ai][0][m][0][j]; xn.y = __builtin_bit_cast(float, x2[0] & 0xffff0000u) + acc[ai][0][m][1][j];
;             xn.z = __builtin_bit_cast(float, x2[1] << 16) + acc[ai][1][m][0][j]; xn.w = __builtin_bit_cast(float, x2[1] & 0xffff0000u) + acc[ai][1][m][1][j];
;             u32x2 o = {pk2(xn.x, xn.y), pk2(xn.z, xn.w)};
;             st_wt(ea.outb + (size_t)row * DM + c0, o);
;             float ss = xn.x * xn.x + xn.y * xn.y + xn.z * xn.z + xn.w * xn.w;
;             ss = row16_sum(ss);
;             if (fr == 0) __hip_atomic_fetch_add(ea.rowsq_out + row, (rsq_t)(ss * RSQ_SCALE), __ATOMIC_RELAXED, __HIP_MEMORY_SCOPE_AGENT);
;           }
	v_add_f32_e32 v248, v46, v248
	v_add_f32_e32 v249, v42, v249
	v_add_f32_e32 v250, v39, v250
	v_add_f32_e32 v251, v35, v251
	v_add_f32_e32 v252, v47, v252
	v_add_f32_e32 v253, v43, v253
	v_cvt_pk_bf16_f32 v132, v238, v239
	v_cvt_pk_bf16_f32 v133, v240, v241
	v_cvt_pk_bf16_f32 v134, v242, v243
	v_cvt_pk_bf16_f32 v135, v244, v245
	v_cvt_pk_bf16_f32 v136, v246, v247
	v_cvt_pk_bf16_f32 v137, v248, v249
	v_cvt_pk_bf16_f32 v156, v250, v251
	v_cvt_pk_bf16_f32 v157, v252, v253
	v_add_u32_e32 v228, 0x90000, v226
	global_store_dwordx2 v228, v[132:133], s[2:3] sc1
	v_add_u32_e32 v227, 0x91000, v226
	global_store_dwordx2 v227, v[134:135], s[2:3] sc1
	v_add_u32_e32 v228, 0x92000, v226
	global_store_dwordx2 v228, v[136:137], s[2:3] sc1
	v_add_u32_e32 v227, 0x93000, v226
	global_store_dwordx2 v227, v[156:157], s[2:3] sc1
	v_pk_mul_f32 v[238:239], v[238:239], v[238:239]
	v_pk_mul_f32 v[240:241], v[240:241], v[240:241]
	v_pk_mul_f32 v[242:243], v[242:243], v[242:243]
	v_pk_mul_f32 v[244:245], v[244:245], v[244:245]
	v_pk_mul_f32 v[246:247], v[246:247], v[246:247]
	v_pk_mul_f32 v[248:249], v[248:249], v[248:249]
	v_pk_mul_f32 v[250:251], v[250:251], v[250:251]
	v_pk_mul_f32 v[252:253], v[252:253], v[252:253]
	v_add_f32_e32 v158, v238, v239
	v_add_f32_e32 v159, v242, v243
	v_add_f32_e32 v160, v246, v247
	v_add_f32_e32 v161, v250, v251
	v_add_f32_e32 v158, v240, v158
	v_add_f32_e32 v159, v244, v159
	v_add_f32_e32 v160, v248, v160
	v_add_f32_e32 v161, v252, v161
	v_add_f32_e32 v158, v241, v158
	v_add_f32_e32 v159, v245, v159
	v_add_f32_e32 v160, v249, v160
	v_add_f32_e32 v161, v253, v161
	v_add_f32_dpp v158, v158, v158 row_ror:8 row_mask:0xf bank_mask:0xf bound_ctrl:1
	v_add_f32_dpp v159, v159, v159 row_ror:8 row_mask:0xf bank_mask:0xf bound_ctrl:1
	v_add_f32_dpp v160, v160, v160 row_ror:8 row_mask:0xf bank_mask:0xf bound_ctrl:1
	v_add_f32_dpp v161, v161, v161 row_ror:8 row_mask:0xf bank_mask:0xf bound_ctrl:1
	v_add_f32_dpp v158, v158, v158 row_ror:4 row_mask:0xf bank_mask:0xf bound_ctrl:1
	v_add_f32_dpp v159, v159, v159 row_ror:4 row_mask:0xf bank_mask:0xf bound_ctrl:1
	v_add_f32_dpp v160, v160, v160 row_ror:4 row_mask:0xf bank_mask:0xf bound_ctrl:1
	v_add_f32_dpp v161, v161, v161 row_ror:4 row_mask:0xf bank_mask:0xf bound_ctrl:1
	v_add_f32_dpp v158, v158, v158 row_ror:2 row_mask:0xf bank_mask:0xf bound_ctrl:1
	v_add_f32_dpp v159, v159, v159 row_ror:2 row_mask:0xf bank_mask:0xf bound_ctrl:1
	v_add_f32_dpp v160, v160, v160 row_ror:2 row_mask:0xf bank_mask:0xf bound_ctrl:1
	v_add_f32_dpp v161, v161, v161 row_ror:2 row_mask:0xf bank_mask:0xf bound_ctrl:1
	v_add_f32_dpp v158, v158, v158 row_ror:1 row_mask:0xf bank_mask:0xf bound_ctrl:1
	v_add_f32_dpp v159, v159, v159 row_ror:1 row_mask:0xf bank_mask:0xf bound_ctrl:1
	v_add_f32_dpp v160, v160, v160 row_ror:1 row_mask:0xf bank_mask:0xf bound_ctrl:1
	v_add_f32_dpp v161, v161, v161 row_ror:1 row_mask:0xf bank_mask:0xf bound_ctrl:1
	v_mov_b32_e32 v254, v158
	v_mov_b32_dpp v254, v159 quad_perm:[0,1,2,3] row_mask:0xf bank_mask:0x2
	v_mov_b32_dpp v254, v160 quad_perm:[0,1,2,3] row_mask:0xf bank_mask:0x4
	v_mov_b32_dpp v254, v161 quad_perm:[0,1,2,3] row_mask:0xf bank_mask:0x8
	v_mul_f32_e32 v254, 0x49800000, v254
	v_trunc_f32_e32 v254, v254
	v_mul_f32_e32 v255, 0x2f800000, v254
	v_floor_f32_e32 v255, v255
	v_fmac_f32_e32 v254, 0xcf800000, v255
	v_cvt_u32_f32_e32 v36, v254
	v_cvt_u32_f32_e32 v37, v255
	v_lshlrev_b32_e32 v238, 16, v210
	v_and_b32_e32 v239, 0xffff0000, v210
	v_lshlrev_b32_e32 v240, 16, v211
	v_and_b32_e32 v241, 0xffff0000, v211
	v_lshlrev_b32_e32 v242, 16, v212
	v_and_b32_e32 v243, 0xffff0000, v212
	v_lshlrev_b32_e32 v244, 16, v213
	v_and_b32_e32 v245, 0xffff0000, v213
	v_lshlrev_b32_e32 v246, 16, v214
	v_and_b32_e32 v247, 0xffff0000, v214
	v_lshlrev_b32_e32 v248, 16, v215
	v_and_b32_e32 v249, 0xffff0000, v215
	v_lshlrev_b32_e32 v250, 16, v216
	v_and_b32_e32 v251, 0xffff0000, v216
	v_lshlrev_b32_e32 v252, 16, v217
	v_and_b32_e32 v253, 0xffff0000, v217
	v_add_f32_e32 v238, v20, v238
	v_add_f32_e32 v239, v16, v239
	v_add_f32_e32 v240, v28, v240
	v_add_f32_e32 v241, v24, v241
	v_add_f32_e32 v242, v21, v242
	v_add_f32_e32 v243, v17, v243
	v_add_f32_e32 v244, v29, v244
	v_add_f32_e32 v245, v25, v245
	v_add_f32_e32 v246, v22, v246
	v_add_f32_e32 v247, v18, v247
	v_add_f32_e32 v248, v30, v248
	v_add_f32_e32 v249, v26, v249
	v_add_f32_e32 v250, v23, v250
	v_add_f32_e32 v251, v19, v251
	v_add_f32_e32 v252, v31, v252
	v_add_f32_e32 v253, v27, v253
	v_cvt_pk_bf16_f32 v132, v238, v239
	v_cvt_pk_bf16_f32 v133, v240, v241
	v_cvt_pk_bf16_f32 v134, v242, v243
	v_cvt_pk_bf16_f32 v135, v244, v245
	v_cvt_pk_bf16_f32 v136, v246, v247
	v_cvt_pk_bf16_f32 v137, v248, v249
	v_cvt_pk_bf16_f32 v156, v250, v251
	v_cvt_pk_bf16_f32 v157, v252, v253
	v_add_u32_e32 v228, 0xa0000, v226
	global_store_dwordx2 v228, v[132:133], s[2:3] sc1
	v_add_u32_e32 v227, 0xa1000, v226
	global_store_dwordx2 v227, v[134:135], s[2:3] sc1
	v_add_u32_e32 v228, 0xa2000, v226
	global_store_dwordx2 v228, v[136:137], s[2:3] sc1
	v_add_u32_e32 v227, 0xa3000, v226
	global_store_dwordx2 v227, v[156:157], s[2:3] sc1
	v_pk_mul_f32 v[238:239], v[238:239], v[238:239]
	v_pk_mul_f32 v[240:241], v[240:241], v[240:241]
	v_pk_mul_f32 v[242:243], v[242:243], v[242:243]
	v_pk_mul_f32 v[244:245], v[244:245], v[244:245]
	v_pk_mul_f32 v[246:247], v[246:247], v[246:247]
	v_pk_mul_f32 v[248:249], v[248:249], v[248:249]
	v_pk_mul_f32 v[250:251], v[250:251], v[250:251]
	v_pk_mul_f32 v[252:253], v[252:253], v[252:253]
	v_add_f32_e32 v158, v238, v239
	v_add_f32_e32 v159, v242, v243
	v_add_f32_e32 v160, v246, v247
	v_add_f32_e32 v161, v250, v251
	v_add_f32_e32 v158, v240, v158
; __device__ __forceinline__ float row16_sum(float v) { DPP_ADD(v, 0x128); DPP_ADD(v, 0x124); DPP_ADD(v, 0x122); DPP_ADD(v, 0x121); return v; }
; template <int EPI, int N, int K>
; __device__ __forceinline__ void gemm_phase(const bf16_t* __restrict__ A, const bf16_t* __restrict__ Bt, const EpiArgs ea) {
;     ...
; #pragma unroll
;       for (int ai = 0; ai < 2; ++ai)
; #pragma unroll
;         for (int m = 0; m < 4; ++m)
; #pragma unroll
;           for (int j = 0; j < 4; ++j) {
;             const int row = brow + ai * 128 + wr * 64 + m * 16 + fq * 4 + j;
;             const u32x2 x2 = *(const u32x2*)(ea.outb + (size_t)row * DM + c0);
;             float4 xn;
;             xn.x = __builtin_bit_cast(float, x2[0] << 16) + acc[ai][0][m][0][j]; xn.y = __builtin_bit_cast(float, x2[0] & 0xffff0000u) + acc[ai][0][m][1][j];
;             xn.z = __builtin_bit_cast(float, x2[1] << 16) + acc[ai][1][m][0][j]; xn.w = __builtin_bit_cast(float, x2[1] & 0xffff0000u) + acc[ai][1][m][1][j];
;             u32x2 o = {pk2(xn.x, xn.y), pk2(xn.z, xn.w)};
;             st_wt(ea.outb + (size_t)row * DM + c0, o);
;             float ss = xn.x * xn.x + xn.y * xn.y + xn.z * xn.z + xn.w * xn.w;
;             ss = row16_sum(ss);
;             if (fr == 0) __hip_atomic_fetch_add(ea.rowsq_out + row, (rsq_t)(ss * RSQ_SCALE), __ATOMIC_RELAXED, __HIP_MEMORY_SCOPE_AGENT);
;           }
	v_add_f32_e32 v159, v244, v159
	v_add_f32_e32 v160, v248, v160
	v_add_f32_e32 v161, v252, v161
	v_add_f32_e32 v158, v241, v158
	v_add_f32_e32 v159, v245, v159
	v_add_f32_e32 v160, v249, v160
	v_add_f32_e32 v161, v253, v161
	v_add_f32_dpp v158, v158, v158 row_ror:8 row_mask:0xf bank_mask:0xf bound_ctrl:1
	v_add_f32_dpp v159, v159, v159 row_ror:8 row_mask:0xf bank_mask:0xf bound_ctrl:1
	v_add_f32_dpp v160, v160, v160 row_ror:8 row_mask:0xf bank_mask:0xf bound_ctrl:1
	v_add_f32_dpp v161, v161, v161 row_ror:8 row_mask:0xf bank_mask:0xf bound_ctrl:1
	v_add_f32_dpp v158, v158, v158 row_ror:4 row_mask:0xf bank_mask:0xf bound_ctrl:1
	v_add_f32_dpp v159, v159, v159 row_ror:4 row_mask:0xf bank_mask:0xf bound_ctrl:1
	v_add_f32_dpp v160, v160, v160 row_ror:4 row_mask:0xf bank_mask:0xf bound_ctrl:1
	v_add_f32_dpp v161, v161, v161 row_ror:4 row_mask:0xf bank_mask:0xf bound_ctrl:1
	v_add_f32_dpp v158, v158, v158 row_ror:2 row_mask:0xf bank_mask:0xf bound_ctrl:1
	v_add_f32_dpp v159, v159, v159 row_ror:2 row_mask:0xf bank_mask:0xf bound_ctrl:1
	v_add_f32_dpp v160, v160, v160 row_ror:2 row_mask:0xf bank_mask:0xf bound_ctrl:1
	v_add_f32_dpp v161, v161, v161 row_ror:2 row_mask:0xf bank_mask:0xf bound_ctrl:1
	v_add_f32_dpp v158, v158, v158 row_ror:1 row_mask:0xf bank_mask:0xf bound_ctrl:1
	v_add_f32_dpp v159, v159, v159 row_ror:1 row_mask:0xf bank_mask:0xf bound_ctrl:1
	v_add_f32_dpp v160, v160, v160 row_ror:1 row_mask:0xf bank_mask:0xf bound_ctrl:1
	v_add_f32_dpp v161, v161, v161 row_ror:1 row_mask:0xf bank_mask:0xf bound_ctrl:1
	v_mov_b32_e32 v254, v158
	v_mov_b32_dpp v254, v159 quad_perm:[0,1,2,3] row_mask:0xf bank_mask:0x2
	v_mov_b32_dpp v254, v160 quad_perm:[0,1,2,3] row_mask:0xf bank_mask:0x4
	v_mov_b32_dpp v254, v161 quad_perm:[0,1,2,3] row_mask:0xf bank_mask:0x8
	v_mul_f32_e32 v254, 0x49800000, v254
	v_trunc_f32_e32 v254, v254
	v_mul_f32_e32 v255, 0x2f800000, v254
	v_floor_f32_e32 v255, v255
	v_fmac_f32_e32 v254, 0xcf800000, v255
	v_cvt_u32_f32_e32 v20, v254
	v_cvt_u32_f32_e32 v21, v255
	v_lshlrev_b32_e32 v238, 16, v218
	v_and_b32_e32 v239, 0xffff0000, v218
	v_lshlrev_b32_e32 v240, 16, v219
	v_and_b32_e32 v241, 0xffff0000, v219
	v_lshlrev_b32_e32 v242, 16, v220
	v_and_b32_e32 v243, 0xffff0000, v220
	v_lshlrev_b32_e32 v244, 16, v221
	v_and_b32_e32 v245, 0xffff0000, v221
	v_lshlrev_b32_e32 v246, 16, v222
	v_and_b32_e32 v247, 0xffff0000, v222
	v_lshlrev_b32_e32 v248, 16, v223
	v_and_b32_e32 v249, 0xffff0000, v223
	v_lshlrev_b32_e32 v250, 16, v224
	v_and_b32_e32 v251, 0xffff0000, v224
	v_lshlrev_b32_e32 v252, 16, v225
	v_and_b32_e32 v253, 0xffff0000, v225
	v_add_f32_e32 v238, v8, v238
	v_add_f32_e32 v239, v12, v239
	v_add_f32_e32 v240, v4, v240
	v_add_f32_e32 v241, v0, v241
	v_add_f32_e32 v242, v9, v242
	v_add_f32_e32 v243, v13, v243
	v_add_f32_e32 v244, v5, v244
	v_add_f32_e32 v245, v1, v245
	v_add_f32_e32 v246, v10, v246
	v_add_f32_e32 v247, v14, v247
	v_add_f32_e32 v248, v6, v248
	v_add_f32_e32 v249, v2, v249
	v_add_f32_e32 v250, v11, v250
	v_add_f32_e32 v251, v15, v251
	v_add_f32_e32 v252, v7, v252
	v_add_f32_e32 v253, v3, v253
	v_cvt_pk_bf16_f32 v132, v238, v239
	v_cvt_pk_bf16_f32 v133, v240, v241
	v_cvt_pk_bf16_f32 v134, v242, v243
	v_cvt_pk_bf16_f32 v135, v244, v245
	v_cvt_pk_bf16_f32 v136, v246, v247
	v_cvt_pk_bf16_f32 v137, v248, v249
	v_cvt_pk_bf16_f32 v156, v250, v251
	v_cvt_pk_bf16_f32 v157, v252, v253
	v_add_u32_e32 v228, 0xb0000, v226
	global_store_dwordx2 v228, v[132:133], s[2:3] sc1
	v_add_u32_e32 v227, 0xb1000, v226
	global_store_dwordx2 v227, v[134:135], s[2:3] sc1
	v_add_u32_e32 v228, 0xb2000, v226
	global_store_dwordx2 v228, v[136:137], s[2:3] sc1
	v_add_u32_e32 v227, 0xb3000, v226
	global_store_dwordx2 v227, v[156:157], s[2:3] sc1
	v_pk_mul_f32 v[238:239], v[238:239], v[238:239]
	v_pk_mul_f32 v[240:241], v[240:241], v[240:241]
	v_pk_mul_f32 v[242:243], v[242:243], v[242:243]
	v_pk_mul_f32 v[244:245], v[244:245], v[244:245]
; __device__ __forceinline__ float row16_sum(float v) { DPP_ADD(v, 0x128); DPP_ADD(v, 0x124); DPP_ADD(v, 0x122); DPP_ADD(v, 0x121); return v; }
; template <int EPI, int N, int K>
; __device__ __forceinline__ void gemm_phase(const bf16_t* __restrict__ A, const bf16_t* __restrict__ Bt, const EpiArgs ea) {
;     ...
; #pragma unroll
;       for (int ai = 0; ai < 2; ++ai)
; #pragma unroll
;         for (int m = 0; m < 4; ++m)
; #pragma unroll
;           for (int j = 0; j < 4; ++j) {
;             const int row = brow + ai * 128 + wr * 64 + m * 16 + fq * 4 + j;
;             const u32x2 x2 = *(const u32x2*)(ea.outb + (size_t)row * DM + c0);
;             float4 xn;
;             xn.x = __builtin_bit_cast(float, x2[0] << 16) + acc[ai][0][m][0][j]; xn.y = __builtin_bit_cast(float, x2[0] & 0xffff0000u) + acc[ai][0][m][1][j];
;             xn.z = __builtin_bit_cast(float, x2[1] << 16) + acc[ai][1][m][0][j]; xn.w = __builtin_bit_cast(float, x2[1] & 0xffff0000u) + acc[ai][1][m][1][j];
;             u32x2 o = {pk2(xn.x, xn.y), pk2(xn.z, xn.w)};
;             st_wt(ea.outb + (size_t)row * DM + c0, o);
;             float ss = xn.x * xn.x + xn.y * xn.y + xn.z * xn.z + xn.w * xn.w;
;             ss = row16_sum(ss);
;             if (fr == 0) __hip_atomic_fetch_add(ea.rowsq_out + row, (rsq_t)(ss * RSQ_SCALE), __ATOMIC_RELAXED, __HIP_MEMORY_SCOPE_AGENT);
;           }
	v_pk_mul_f32 v[246:247], v[246:247], v[246:247]
	v_pk_mul_f32 v[248:249], v[248:249], v[248:249]
	v_pk_mul_f32 v[250:251], v[250:251], v[250:251]
	v_pk_mul_f32 v[252:253], v[252:253], v[252:253]
	v_add_f32_e32 v158, v238, v239
	v_add_f32_e32 v159, v242, v243
	v_add_f32_e32 v160, v246, v247
	v_add_f32_e32 v161, v250, v251
	v_add_f32_e32 v158, v240, v158
	v_add_f32_e32 v159, v244, v159
	v_add_f32_e32 v160, v248, v160
	v_add_f32_e32 v161, v252, v161
	v_add_f32_e32 v158, v241, v158
	v_add_f32_e32 v159, v245, v159
	v_add_f32_e32 v160, v249, v160
	v_add_f32_e32 v161, v253, v161
	v_add_f32_dpp v158, v158, v158 row_ror:8 row_mask:0xf bank_mask:0xf bound_ctrl:1
	v_add_f32_dpp v159, v159, v159 row_ror:8 row_mask:0xf bank_mask:0xf bound_ctrl:1
	v_add_f32_dpp v160, v160, v160 row_ror:8 row_mask:0xf bank_mask:0xf bound_ctrl:1
	v_add_f32_dpp v161, v161, v161 row_ror:8 row_mask:0xf bank_mask:0xf bound_ctrl:1
	v_add_f32_dpp v158, v158, v158 row_ror:4 row_mask:0xf bank_mask:0xf bound_ctrl:1
	v_add_f32_dpp v159, v159, v159 row_ror:4 row_mask:0xf bank_mask:0xf bound_ctrl:1
	v_add_f32_dpp v160, v160, v160 row_ror:4 row_mask:0xf bank_mask:0xf bound_ctrl:1
	v_add_f32_dpp v161, v161, v161 row_ror:4 row_mask:0xf bank_mask:0xf bound_ctrl:1
	v_add_f32_dpp v158, v158, v158 row_ror:2 row_mask:0xf bank_mask:0xf bound_ctrl:1
	v_add_f32_dpp v159, v159, v159 row_ror:2 row_mask:0xf bank_mask:0xf bound_ctrl:1
	v_add_f32_dpp v160, v160, v160 row_ror:2 row_mask:0xf bank_mask:0xf bound_ctrl:1
	v_add_f32_dpp v161, v161, v161 row_ror:2 row_mask:0xf bank_mask:0xf bound_ctrl:1
	v_add_f32_dpp v158, v158, v158 row_ror:1 row_mask:0xf bank_mask:0xf bound_ctrl:1
	v_add_f32_dpp v159, v159, v159 row_ror:1 row_mask:0xf bank_mask:0xf bound_ctrl:1
	v_add_f32_dpp v160, v160, v160 row_ror:1 row_mask:0xf bank_mask:0xf bound_ctrl:1
	v_add_f32_dpp v161, v161, v161 row_ror:1 row_mask:0xf bank_mask:0xf bound_ctrl:1
	v_mov_b32_e32 v254, v158
	v_mov_b32_dpp v254, v159 quad_perm:[0,1,2,3] row_mask:0xf bank_mask:0x2
	v_mov_b32_dpp v254, v160 quad_perm:[0,1,2,3] row_mask:0xf bank_mask:0x4
	v_mov_b32_dpp v254, v161 quad_perm:[0,1,2,3] row_mask:0xf bank_mask:0x8
	v_mul_f32_e32 v254, 0x49800000, v254
	v_trunc_f32_e32 v254, v254
	v_mul_f32_e32 v255, 0x2f800000, v254
	v_floor_f32_e32 v255, v255
	v_fmac_f32_e32 v254, 0xcf800000, v255
	v_cvt_u32_f32_e32 v8, v254
	v_cvt_u32_f32_e32 v9, v255
	v_and_b32_e32 v227, 12, v145
	v_cmp_eq_u32_e32 vcc, 0, v227
	s_and_b64 exec, exec, vcc
	ds_write_b64 v229, v[116:117]
	ds_write_b64 v229, v[100:101] offset:512
	ds_write_b64 v229, v[84:85] offset:1024
	ds_write_b64 v229, v[68:69] offset:1536
	ds_write_b64 v229, v[52:53] offset:2048
	ds_write_b64 v229, v[36:37] offset:2560
	ds_write_b64 v229, v[20:21] offset:3072
	ds_write_b64 v229, v[8:9] offset:3584
	s_mov_b64 exec, -1
	v_bfe_u32 v227, v146, 2, 2
	v_bfe_u32 v228, v145, 2, 4
	v_lshl_add_u32 v227, v227, 4, v228
	v_lshrrev_b32_e32 v228, 6, v145
	v_lshl_add_u32 v228, v228, 5, v227
	v_lshrrev_b32_e32 v230, 6, v146
	v_lshlrev_b32_e32 v231, 12, v230
	v_lshl_add_u32 v231, v228, 5, v231
	v_add_u32_e32 v231, 0x20410, v231
	v_cmp_gt_u32_e32 vcc, 32, v227
	v_lshrrev_b32_e32 v227, 6, v228
	v_lshlrev_b32_e32 v227, 7, v227
	v_and_b32_e32 v228, 63, v228
	v_add3_u32 v227, v227, v228, s31
	v_lshl_add_u32 v227, v230, 6, v227
	v_lshlrev_b32_e32 v227, 3, v227
	s_waitcnt lgkmcnt(0)
	s_barrier
	s_and_b64 exec, exec, vcc
	ds_read_b128 v[238:241], v231
	ds_read_b128 v[242:245], v231 offset:16
	s_waitcnt lgkmcnt(0)
	v_add_co_u32_e32 v246, vcc, v238, v240
	s_nop 1
	v_addc_co_u32_e32 v247, vcc, v239, v241, vcc
	v_add_co_u32_e32 v246, vcc, v246, v242
	s_nop 1
	v_addc_co_u32_e32 v247, vcc, v247, v243, vcc
	v_add_co_u32_e32 v246, vcc, v246, v244
	s_nop 1
	v_addc_co_u32_e32 v247, vcc, v247, v245, vcc
	global_atomic_add_x2 v227, v[246:247], s[0:1]
	s_mov_b64 exec, -1
	s_mov_b64 s[2:3], -1
	s_branch .LBB0_384

; __device__ __forceinline__ float row16_sum(float v) { DPP_ADD(v, 0x128); DPP_ADD(v, 0x124); DPP_ADD(v, 0x122); DPP_ADD(v, 0x121); return v; }
; template <int EPI, int N, int K>
; __device__ __forceinline__ void gemm_phase(const bf16_t* __restrict__ A, const bf16_t* __restrict__ Bt, const EpiArgs ea) {
;     ...
; #pragma unroll
;       for (int ai = 0; ai < 2; ++ai)
; #pragma unroll
;         for (int m = 0; m < 4; ++m)
; #pragma unroll
;           for (int j = 0; j < 4; ++j) {
;             const int row = brow + ai * 128 + wr * 64 + m * 16 + fq * 4 + j;
;             const u32x2 x2 = *(const u32x2*)(ea.outb + (size_t)row * DM + c0);
;             float4 xn;
;             xn.x = __builtin_bit_cast(float, x2[0] << 16) + acc[ai][0][m][0][j]; xn.y = __builtin_bit_cast(float, x2[0] & 0xffff0000u) + acc[ai][0][m][1][j];
;             xn.z = __builtin_bit_cast(float, x2[1] << 16) + acc[ai][1][m][0][j]; xn.w = __builtin_bit_cast(float, x2[1] & 0xffff0000u) + acc[ai][1][m][1][j];
;             u32x2 o = {pk2(xn.x, xn.y), pk2(xn.z, xn.w)};
;             st_wt(ea.outb + (size_t)row * DM + c0, o);
;             float ss = xn.x * xn.x + xn.y * xn.y + xn.z * xn.z + xn.w * xn.w;
;             ss = row16_sum(ss);
;             if (fr == 0) __hip_atomic_fetch_add(ea.rowsq_out + row, (rsq_t)(ss * RSQ_SCALE), __ATOMIC_RELAXED, __HIP_MEMORY_SCOPE_AGENT);
;           }
.LBB0_573:
	v_readlane_b32 s2, v236, 14
	v_readlane_b32 s3, v236, 15
	v_lshrrev_b32_e32 v227, 6, v146
	v_lshlrev_b32_e32 v229, 12, v227
	v_bfe_u32 v227, v146, 2, 2
	v_lshl_add_u32 v229, v227, 7, v229
	v_bfe_u32 v227, v145, 4, 2
	v_lshl_add_u32 v229, v227, 5, v229
	v_lshrrev_b32_e32 v227, 6, v145
	v_lshl_add_u32 v229, v227, 3, v229
	v_add_u32_e32 v229, 0x20410, v229
	v_lshlrev_b32_e32 v238, 16, v162
	v_and_b32_e32 v239, 0xffff0000, v162
	v_lshlrev_b32_e32 v240, 16, v163
	v_and_b32_e32 v241, 0xffff0000, v163
	v_lshlrev_b32_e32 v242, 16, v164
	v_and_b32_e32 v243, 0xffff0000, v164
	v_lshlrev_b32_e32 v244, 16, v165
	v_and_b32_e32 v245, 0xffff0000, v165
	v_lshlrev_b32_e32 v246, 16, v166
	v_and_b32_e32 v247, 0xffff0000, v166
	v_lshlrev_b32_e32 v248, 16, v167
	v_and_b32_e32 v249, 0xffff0000, v167
	v_lshlrev_b32_e32 v250, 16, v168
	v_and_b32_e32 v251, 0xffff0000, v168
	v_lshlrev_b32_e32 v252, 16, v169
	v_and_b32_e32 v253, 0xffff0000, v169
	v_add_f32_e32 v238, v116, v238
	v_add_f32_e32 v239, v112, v239
	v_add_f32_e32 v240, v124, v240
	v_add_f32_e32 v241, v120, v241
	v_add_f32_e32 v242, v117, v242
	v_add_f32_e32 v243, v113, v243
	v_add_f32_e32 v244, v125, v244
	v_add_f32_e32 v245, v121, v245
	v_add_f32_e32 v246, v118, v246
	v_add_f32_e32 v247, v114, v247
	v_add_f32_e32 v248, v126, v248
	v_add_f32_e32 v249, v122, v249
	v_add_f32_e32 v250, v119, v250
	v_add_f32_e32 v251, v115, v251
	v_add_f32_e32 v252, v127, v252
	v_add_f32_e32 v253, v123, v253
	v_cvt_pk_bf16_f32 v132, v238, v239
	v_cvt_pk_bf16_f32 v133, v240, v241
	v_cvt_pk_bf16_f32 v134, v242, v243
	v_cvt_pk_bf16_f32 v135, v244, v245
	v_cvt_pk_bf16_f32 v136, v246, v247
	v_cvt_pk_bf16_f32 v137, v248, v249
	v_cvt_pk_bf16_f32 v156, v250, v251
	v_cvt_pk_bf16_f32 v157, v252, v253
	global_store_dwordx2 v226, v[132:133], s[2:3] sc1
	v_add_u32_e32 v227, 0x1000, v226
	global_store_dwordx2 v227, v[134:135], s[2:3] sc1
	v_add_u32_e32 v228, 0x2000, v226
	global_store_dwordx2 v228, v[136:137], s[2:3] sc1
	v_add_u32_e32 v227, 0x3000, v226
	global_store_dwordx2 v227, v[156:157], s[2:3] sc1
	v_pk_mul_f32 v[238:239], v[238:239], v[238:239]
	v_pk_mul_f32 v[240:241], v[240:241], v[240:241]
	v_pk_mul_f32 v[242:243], v[242:243], v[242:243]
	v_pk_mul_f32 v[244:245], v[244:245], v[244:245]
	v_pk_mul_f32 v[246:247], v[246:247], v[246:247]
	v_pk_mul_f32 v[248:249], v[248:249], v[248:249]
	v_pk_mul_f32 v[250:251], v[250:251], v[250:251]
	v_pk_mul_f32 v[252:253], v[252:253], v[252:253]
	v_add_f32_e32 v158, v238, v239
	v_add_f32_e32 v159, v242, v243
	v_add_f32_e32 v160, v246, v247
	v_add_f32_e32 v161, v250, v251
	v_add_f32_e32 v158, v240, v158
	v_add_f32_e32 v159, v244, v159
	v_add_f32_e32 v160, v248, v160
	v_add_f32_e32 v161, v252, v161
	v_add_f32_e32 v158, v241, v158
	v_add_f32_e32 v159, v245, v159
	v_add_f32_e32 v160, v249, v160
	v_add_f32_e32 v161, v253, v161
	v_add_f32_dpp v158, v158, v158 row_ror:8 row_mask:0xf bank_mask:0xf bound_ctrl:1
	v_add_f32_dpp v159, v159, v159 row_ror:8 row_mask:0xf bank_mask:0xf bound_ctrl:1
	v_add_f32_dpp v160, v160, v160 row_ror:8 row_mask:0xf bank_mask:0xf bound_ctrl:1
	v_add_f32_dpp v161, v161, v161 row_ror:8 row_mask:0xf bank_mask:0xf bound_ctrl:1
	v_add_f32_dpp v158, v158, v158 row_ror:4 row_mask:0xf bank_mask:0xf bound_ctrl:1
	v_add_f32_dpp v159, v159, v159 row_ror:4 row_mask:0xf bank_mask:0xf bound_ctrl:1
	v_add_f32_dpp v160, v160, v160 row_ror:4 row_mask:0xf bank_mask:0xf bound_ctrl:1
	v_add_f32_dpp v161, v161, v161 row_ror:4 row_mask:0xf bank_mask:0xf bound_ctrl:1
	v_add_f32_dpp v158, v158, v158 row_ror:2 row_mask:0xf bank_mask:0xf bound_ctrl:1
	v_add_f32_dpp v159, v159, v159 row_ror:2 row_mask:0xf bank_mask:0xf bound_ctrl:1
	v_add_f32_dpp v160, v160, v160 row_ror:2 row_mask:0xf bank_mask:0xf bound_ctrl:1
	v_add_f32_dpp v161, v161, v161 row_ror:2 row_mask:0xf bank_mask:0xf bound_ctrl:1
	v_add_f32_dpp v158, v158, v158 row_ror:1 row_mask:0xf bank_mask:0xf bound_ctrl:1
	v_add_f32_dpp v159, v159, v159 row_ror:1 row_mask:0xf bank_mask:0xf bound_ctrl:1
	v_add_f32_dpp v160, v160, v160 row_ror:1 row_mask:0xf bank_mask:0xf bound_ctrl:1
	v_add_f32_dpp v161, v161, v161 row_ror:1 row_mask:0xf bank_mask:0xf bound_ctrl:1
	v_mov_b32_e32 v254, v158
	v_mov_b32_dpp v254, v159 quad_perm:[0,1,2,3] row_mask:0xf bank_mask:0x2
	v_mov_b32_dpp v254, v160 quad_perm:[0,1,2,3] row_mask:0xf bank_mask:0x4
	v_mov_b32_dpp v254, v161 quad_perm:[0,1,2,3] row_mask:0xf bank_mask:0x8
	v_mul_f32_e32 v254, 0x49800000, v254
	v_trunc_f32_e32 v254, v254
	v_mul_f32_e32 v255, 0x2f800000, v254
	v_floor_f32_e32 v255, v255
	v_fmac_f32_e32 v254, 0xcf800000, v255
	v_cvt_u32_f32_e32 v116, v254
	v_cvt_u32_f32_e32 v117, v255
	v_lshlrev_b32_e32 v238, 16, v170
	v_and_b32_e32 v239, 0xffff0000, v170
	v_lshlrev_b32_e32 v240, 16, v171
	v_and_b32_e32 v241, 0xffff0000, v171
	v_lshlrev_b32_e32 v242, 16, v172
	v_and_b32_e32 v243, 0xffff0000, v172
	v_lshlrev_b32_e32 v244, 16, v173
	v_and_b32_e32 v245, 0xffff0000, v173
	v_lshlrev_b32_e32 v246, 16, v174
	v_and_b32_e32 v247, 0xffff0000, v174
	v_lshlrev_b32_e32 v248, 16, v175
	v_and_b32_e32 v249, 0xffff0000, v175
	v_lshlrev_b32_e32 v250, 16, v176
	v_and_b32_e32 v251, 0xffff0000, v176
	v_lshlrev_b32_e32 v252, 16, v177
	v_and_b32_e32 v253, 0xffff0000, v177
	v_add_f32_e32 v238, v100, v238
	v_add_f32_e32 v239, v96, v239
	v_add_f32_e32 v240, v108, v240
	v_add_f32_e32 v241, v104, v241
	v_add_f32_e32 v242, v101, v242
	v_add_f32_e32 v243, v97, v243
	v_add_f32_e32 v244, v109, v244
	v_add_f32_e32 v245, v105, v245
	v_add_f32_e32 v246, v102, v246
	v_add_f32_e32 v247, v98, v247
	v_add_f32_e32 v248, v110, v248
	v_add_f32_e32 v249, v106, v249
	v_add_f32_e32 v250, v103, v250
	v_add_f32_e32 v251, v99, v251
; __device__ __forceinline__ float row16_sum(float v) { DPP_ADD(v, 0x128); DPP_ADD(v, 0x124); DPP_ADD(v, 0x122); DPP_ADD(v, 0x121); return v; }
; template <int EPI, int N, int K>
; __device__ __forceinline__ void gemm_phase(const bf16_t* __restrict__ A, const bf16_t* __restrict__ Bt, const EpiArgs ea) {
;     ...
; #pragma unroll
;       for (int ai = 0; ai < 2; ++ai)
; #pragma unroll
;         for (int m = 0; m < 4; ++m)
; #pragma unroll
;           for (int j = 0; j < 4; ++j) {
;             const int row = brow + ai * 128 + wr * 64 + m * 16 + fq * 4 + j;
;             const u32x2 x2 = *(const u32x2*)(ea.outb + (size_t)row * DM + c0);
;             float4 xn;
;             xn.x = __builtin_bit_cast(float, x2[0] << 16) + acc[ai][0][m][0][j]; xn.y = __builtin_bit_cast(float, x2[0] & 0xffff0000u) + acc[ai][0][m][1][j];
;             xn.z = __builtin_bit_cast(float, x2[1] << 16) + acc[ai][1][m][0][j]; xn.w = __builtin_bit_cast(float, x2[1] & 0xffff0000u) + acc[ai][1][m][1][j];
;             u32x2 o = {pk2(xn.x, xn.y), pk2(xn.z, xn.w)};
;             st_wt(ea.outb + (size_t)row * DM + c0, o);
;             float ss = xn.x * xn.x + xn.y * xn.y + xn.z * xn.z + xn.w * xn.w;
;             ss = row16_sum(ss);
;             if (fr == 0) __hip_atomic_fetch_add(ea.rowsq_out + row, (rsq_t)(ss * RSQ_SCALE), __ATOMIC_RELAXED, __HIP_MEMORY_SCOPE_AGENT);
;           }
	v_add_f32_e32 v252, v111, v252
	v_add_f32_e32 v253, v107, v253
	v_cvt_pk_bf16_f32 v132, v238, v239
	v_cvt_pk_bf16_f32 v133, v240, v241
	v_cvt_pk_bf16_f32 v134, v242, v243
	v_cvt_pk_bf16_f32 v135, v244, v245
	v_cvt_pk_bf16_f32 v136, v246, v247
	v_cvt_pk_bf16_f32 v137, v248, v249
	v_cvt_pk_bf16_f32 v156, v250, v251
	v_cvt_pk_bf16_f32 v157, v252, v253
	v_add_u32_e32 v228, 0x10000, v226
	global_store_dwordx2 v228, v[132:133], s[2:3] sc1
	v_add_u32_e32 v227, 0x11000, v226
	global_store_dwordx2 v227, v[134:135], s[2:3] sc1
	v_add_u32_e32 v228, 0x12000, v226
	global_store_dwordx2 v228, v[136:137], s[2:3] sc1
	v_add_u32_e32 v227, 0x13000, v226
	global_store_dwordx2 v227, v[156:157], s[2:3] sc1
	v_pk_mul_f32 v[238:239], v[238:239], v[238:239]
	v_pk_mul_f32 v[240:241], v[240:241], v[240:241]
	v_pk_mul_f32 v[242:243], v[242:243], v[242:243]
	v_pk_mul_f32 v[244:245], v[244:245], v[244:245]
	v_pk_mul_f32 v[246:247], v[246:247], v[246:247]
	v_pk_mul_f32 v[248:249], v[248:249], v[248:249]
	v_pk_mul_f32 v[250:251], v[250:251], v[250:251]
	v_pk_mul_f32 v[252:253], v[252:253], v[252:253]
	v_add_f32_e32 v158, v238, v239
	v_add_f32_e32 v159, v242, v243
	v_add_f32_e32 v160, v246, v247
	v_add_f32_e32 v161, v250, v251
	v_add_f32_e32 v158, v240, v158
	v_add_f32_e32 v159, v244, v159
	v_add_f32_e32 v160, v248, v160
	v_add_f32_e32 v161, v252, v161
	v_add_f32_e32 v158, v241, v158
	v_add_f32_e32 v159, v245, v159
	v_add_f32_e32 v160, v249, v160
	v_add_f32_e32 v161, v253, v161
	v_add_f32_dpp v158, v158, v158 row_ror:8 row_mask:0xf bank_mask:0xf bound_ctrl:1
	v_add_f32_dpp v159, v159, v159 row_ror:8 row_mask:0xf bank_mask:0xf bound_ctrl:1
	v_add_f32_dpp v160, v160, v160 row_ror:8 row_mask:0xf bank_mask:0xf bound_ctrl:1
	v_add_f32_dpp v161, v161, v161 row_ror:8 row_mask:0xf bank_mask:0xf bound_ctrl:1
	v_add_f32_dpp v158, v158, v158 row_ror:4 row_mask:0xf bank_mask:0xf bound_ctrl:1
	v_add_f32_dpp v159, v159, v159 row_ror:4 row_mask:0xf bank_mask:0xf bound_ctrl:1
	v_add_f32_dpp v160, v160, v160 row_ror:4 row_mask:0xf bank_mask:0xf bound_ctrl:1
	v_add_f32_dpp v161, v161, v161 row_ror:4 row_mask:0xf bank_mask:0xf bound_ctrl:1
	v_add_f32_dpp v158, v158, v158 row_ror:2 row_mask:0xf bank_mask:0xf bound_ctrl:1
	v_add_f32_dpp v159, v159, v159 row_ror:2 row_mask:0xf bank_mask:0xf bound_ctrl:1
	v_add_f32_dpp v160, v160, v160 row_ror:2 row_mask:0xf bank_mask:0xf bound_ctrl:1
	v_add_f32_dpp v161, v161, v161 row_ror:2 row_mask:0xf bank_mask:0xf bound_ctrl:1
	v_add_f32_dpp v158, v158, v158 row_ror:1 row_mask:0xf bank_mask:0xf bound_ctrl:1
	v_add_f32_dpp v159, v159, v159 row_ror:1 row_mask:0xf bank_mask:0xf bound_ctrl:1
	v_add_f32_dpp v160, v160, v160 row_ror:1 row_mask:0xf bank_mask:0xf bound_ctrl:1
	v_add_f32_dpp v161, v161, v161 row_ror:1 row_mask:0xf bank_mask:0xf bound_ctrl:1
	v_mov_b32_e32 v254, v158
	v_mov_b32_dpp v254, v159 quad_perm:[0,1,2,3] row_mask:0xf bank_mask:0x2
	v_mov_b32_dpp v254, v160 quad_perm:[0,1,2,3] row_mask:0xf bank_mask:0x4
	v_mov_b32_dpp v254, v161 quad_perm:[0,1,2,3] row_mask:0xf bank_mask:0x8
	v_mul_f32_e32 v254, 0x49800000, v254
	v_trunc_f32_e32 v254, v254
	v_mul_f32_e32 v255, 0x2f800000, v254
	v_floor_f32_e32 v255, v255
	v_fmac_f32_e32 v254, 0xcf800000, v255
	v_cvt_u32_f32_e32 v100, v254
	v_cvt_u32_f32_e32 v101, v255
	v_lshlrev_b32_e32 v238, 16, v178
	v_and_b32_e32 v239, 0xffff0000, v178
	v_lshlrev_b32_e32 v240, 16, v179
	v_and_b32_e32 v241, 0xffff0000, v179
	v_lshlrev_b32_e32 v242, 16, v180
	v_and_b32_e32 v243, 0xffff0000, v180
	v_lshlrev_b32_e32 v244, 16, v181
	v_and_b32_e32 v245, 0xffff0000, v181
	v_lshlrev_b32_e32 v246, 16, v182
	v_and_b32_e32 v247, 0xffff0000, v182
	v_lshlrev_b32_e32 v248, 16, v183
	v_and_b32_e32 v249, 0xffff0000, v183
	v_lshlrev_b32_e32 v250, 16, v184
	v_and_b32_e32 v251, 0xffff0000, v184
	v_lshlrev_b32_e32 v252, 16, v185
	v_and_b32_e32 v253, 0xffff0000, v185
	v_add_f32_e32 v238, v84, v238
	v_add_f32_e32 v239, v80, v239
	v_add_f32_e32 v240, v92, v240
	v_add_f32_e32 v241, v88, v241
	v_add_f32_e32 v242, v85, v242
	v_add_f32_e32 v243, v81, v243
	v_add_f32_e32 v244, v93, v244
	v_add_f32_e32 v245, v89, v245
	v_add_f32_e32 v246, v86, v246
	v_add_f32_e32 v247, v82, v247
	v_add_f32_e32 v248, v94, v248
	v_add_f32_e32 v249, v90, v249
	v_add_f32_e32 v250, v87, v250
	v_add_f32_e32 v251, v83, v251
	v_add_f32_e32 v252, v95, v252
	v_add_f32_e32 v253, v91, v253
	v_cvt_pk_bf16_f32 v132, v238, v239
	v_cvt_pk_bf16_f32 v133, v240, v241
	v_cvt_pk_bf16_f32 v134, v242, v243
	v_cvt_pk_bf16_f32 v135, v244, v245
	v_cvt_pk_bf16_f32 v136, v246, v247
	v_cvt_pk_bf16_f32 v137, v248, v249
	v_cvt_pk_bf16_f32 v156, v250, v251
	v_cvt_pk_bf16_f32 v157, v252, v253
	v_add_u32_e32 v228, 0x20000, v226
	global_store_dwordx2 v228, v[132:133], s[2:3] sc1
	v_add_u32_e32 v227, 0x21000, v226
	global_store_dwordx2 v227, v[134:135], s[2:3] sc1
	v_add_u32_e32 v228, 0x22000, v226
	global_store_dwordx2 v228, v[136:137], s[2:3] sc1
	v_add_u32_e32 v227, 0x23000, v226
	global_store_dwordx2 v227, v[156:157], s[2:3] sc1
	v_pk_mul_f32 v[238:239], v[238:239], v[238:239]
	v_pk_mul_f32 v[240:241], v[240:241], v[240:241]
	v_pk_mul_f32 v[242:243], v[242:243], v[242:243]
	v_pk_mul_f32 v[244:245], v[244:245], v[244:245]
	v_pk_mul_f32 v[246:247], v[246:247], v[246:247]
	v_pk_mul_f32 v[248:249], v[248:249], v[248:249]
	v_pk_mul_f32 v[250:251], v[250:251], v[250:251]
	v_pk_mul_f32 v[252:253], v[252:253], v[252:253]
	v_add_f32_e32 v158, v238, v239
	v_add_f32_e32 v159, v242, v243
	v_add_f32_e32 v160, v246, v247
	v_add_f32_e32 v161, v250, v251
	v_add_f32_e32 v158, v240, v158
	v_add_f32_e32 v159, v244, v159
	v_add_f32_e32 v160, v248, v160
	v_add_f32_e32 v161, v252, v161
	v_add_f32_e32 v158, v241, v158
; __device__ __forceinline__ float row16_sum(float v) { DPP_ADD(v, 0x128); DPP_ADD(v, 0x124); DPP_ADD(v, 0x122); DPP_ADD(v, 0x121); return v; }
; template <int EPI, int N, int K>
; __device__ __forceinline__ void gemm_phase(const bf16_t* __restrict__ A, const bf16_t* __restrict__ Bt, const EpiArgs ea) {
;     ...
; #pragma unroll
;       for (int ai = 0; ai < 2; ++ai)
; #pragma unroll
;         for (int m = 0; m < 4; ++m)
; #pragma unroll
;           for (int j = 0; j < 4; ++j) {
;             const int row = brow + ai * 128 + wr * 64 + m * 16 + fq * 4 + j;
;             const u32x2 x2 = *(const u32x2*)(ea.outb + (size_t)row * DM + c0);
;             float4 xn;
;             xn.x = __builtin_bit_cast(float, x2[0] << 16) + acc[ai][0][m][0][j]; xn.y = __builtin_bit_cast(float, x2[0] & 0xffff0000u) + acc[ai][0][m][1][j];
;             xn.z = __builtin_bit_cast(float, x2[1] << 16) + acc[ai][1][m][0][j]; xn.w = __builtin_bit_cast(float, x2[1] & 0xffff0000u) + acc[ai][1][m][1][j];
;             u32x2 o = {pk2(xn.x, xn.y), pk2(xn.z, xn.w)};
;             st_wt(ea.outb + (size_t)row * DM + c0, o);
;             float ss = xn.x * xn.x + xn.y * xn.y + xn.z * xn.z + xn.w * xn.w;
;             ss = row16_sum(ss);
;             if (fr == 0) __hip_atomic_fetch_add(ea.rowsq_out + row, (rsq_t)(ss * RSQ_SCALE), __ATOMIC_RELAXED, __HIP_MEMORY_SCOPE_AGENT);
;           }
	v_add_f32_e32 v159, v245, v159
	v_add_f32_e32 v160, v249, v160
	v_add_f32_e32 v161, v253, v161
	v_add_f32_dpp v158, v158, v158 row_ror:8 row_mask:0xf bank_mask:0xf bound_ctrl:1
	v_add_f32_dpp v159, v159, v159 row_ror:8 row_mask:0xf bank_mask:0xf bound_ctrl:1
	v_add_f32_dpp v160, v160, v160 row_ror:8 row_mask:0xf bank_mask:0xf bound_ctrl:1
	v_add_f32_dpp v161, v161, v161 row_ror:8 row_mask:0xf bank_mask:0xf bound_ctrl:1
	v_add_f32_dpp v158, v158, v158 row_ror:4 row_mask:0xf bank_mask:0xf bound_ctrl:1
	v_add_f32_dpp v159, v159, v159 row_ror:4 row_mask:0xf bank_mask:0xf bound_ctrl:1
	v_add_f32_dpp v160, v160, v160 row_ror:4 row_mask:0xf bank_mask:0xf bound_ctrl:1
	v_add_f32_dpp v161, v161, v161 row_ror:4 row_mask:0xf bank_mask:0xf bound_ctrl:1
	v_add_f32_dpp v158, v158, v158 row_ror:2 row_mask:0xf bank_mask:0xf bound_ctrl:1
	v_add_f32_dpp v159, v159, v159 row_ror:2 row_mask:0xf bank_mask:0xf bound_ctrl:1
	v_add_f32_dpp v160, v160, v160 row_ror:2 row_mask:0xf bank_mask:0xf bound_ctrl:1
	v_add_f32_dpp v161, v161, v161 row_ror:2 row_mask:0xf bank_mask:0xf bound_ctrl:1
	v_add_f32_dpp v158, v158, v158 row_ror:1 row_mask:0xf bank_mask:0xf bound_ctrl:1
	v_add_f32_dpp v159, v159, v159 row_ror:1 row_mask:0xf bank_mask:0xf bound_ctrl:1
	v_add_f32_dpp v160, v160, v160 row_ror:1 row_mask:0xf bank_mask:0xf bound_ctrl:1
	v_add_f32_dpp v161, v161, v161 row_ror:1 row_mask:0xf bank_mask:0xf bound_ctrl:1
	v_mov_b32_e32 v254, v158
	v_mov_b32_dpp v254, v159 quad_perm:[0,1,2,3] row_mask:0xf bank_mask:0x2
	v_mov_b32_dpp v254, v160 quad_perm:[0,1,2,3] row_mask:0xf bank_mask:0x4
	v_mov_b32_dpp v254, v161 quad_perm:[0,1,2,3] row_mask:0xf bank_mask:0x8
	v_mul_f32_e32 v254, 0x49800000, v254
	v_trunc_f32_e32 v254, v254
	v_mul_f32_e32 v255, 0x2f800000, v254
	v_floor_f32_e32 v255, v255
	v_fmac_f32_e32 v254, 0xcf800000, v255
	v_cvt_u32_f32_e32 v84, v254
	v_cvt_u32_f32_e32 v85, v255
	v_lshlrev_b32_e32 v238, 16, v186
	v_and_b32_e32 v239, 0xffff0000, v186
	v_lshlrev_b32_e32 v240, 16, v187
	v_and_b32_e32 v241, 0xffff0000, v187
	v_lshlrev_b32_e32 v242, 16, v188
	v_and_b32_e32 v243, 0xffff0000, v188
	v_lshlrev_b32_e32 v244, 16, v189
	v_and_b32_e32 v245, 0xffff0000, v189
	v_lshlrev_b32_e32 v246, 16, v190
	v_and_b32_e32 v247, 0xffff0000, v190
	v_lshlrev_b32_e32 v248, 16, v191
	v_and_b32_e32 v249, 0xffff0000, v191
	v_lshlrev_b32_e32 v250, 16, v192
	v_and_b32_e32 v251, 0xffff0000, v192
	v_lshlrev_b32_e32 v252, 16, v193
	v_and_b32_e32 v253, 0xffff0000, v193
	v_add_f32_e32 v238, v68, v238
	v_add_f32_e32 v239, v64, v239
	v_add_f32_e32 v240, v76, v240
	v_add_f32_e32 v241, v72, v241
	v_add_f32_e32 v242, v69, v242
	v_add_f32_e32 v243, v65, v243
	v_add_f32_e32 v244, v77, v244
	v_add_f32_e32 v245, v73, v245
	v_add_f32_e32 v246, v70, v246
	v_add_f32_e32 v247, v66, v247
	v_add_f32_e32 v248, v78, v248
	v_add_f32_e32 v249, v74, v249
	v_add_f32_e32 v250, v71, v250
	v_add_f32_e32 v251, v67, v251
	v_add_f32_e32 v252, v79, v252
	v_add_f32_e32 v253, v75, v253
	v_cvt_pk_bf16_f32 v132, v238, v239
	v_cvt_pk_bf16_f32 v133, v240, v241
	v_cvt_pk_bf16_f32 v134, v242, v243
	v_cvt_pk_bf16_f32 v135, v244, v245
	v_cvt_pk_bf16_f32 v136, v246, v247
	v_cvt_pk_bf16_f32 v137, v248, v249
	v_cvt_pk_bf16_f32 v156, v250, v251
	v_cvt_pk_bf16_f32 v157, v252, v253
	v_add_u32_e32 v228, 0x30000, v226
	global_store_dwordx2 v228, v[132:133], s[2:3] sc1
	v_add_u32_e32 v227, 0x31000, v226
	global_store_dwordx2 v227, v[134:135], s[2:3] sc1
	v_add_u32_e32 v228, 0x32000, v226
	global_store_dwordx2 v228, v[136:137], s[2:3] sc1
	v_add_u32_e32 v227, 0x33000, v226
	global_store_dwordx2 v227, v[156:157], s[2:3] sc1
	v_pk_mul_f32 v[238:239], v[238:239], v[238:239]
	v_pk_mul_f32 v[240:241], v[240:241], v[240:241]
	v_pk_mul_f32 v[242:243], v[242:243], v[242:243]
	v_pk_mul_f32 v[244:245], v[244:245], v[244:245]
	v_pk_mul_f32 v[246:247], v[246:247], v[246:247]
	v_pk_mul_f32 v[248:249], v[248:249], v[248:249]
	v_pk_mul_f32 v[250:251], v[250:251], v[250:251]
	v_pk_mul_f32 v[252:253], v[252:253], v[252:253]
	v_add_f32_e32 v158, v238, v239
	v_add_f32_e32 v159, v242, v243
	v_add_f32_e32 v160, v246, v247
	v_add_f32_e32 v161, v250, v251
	v_add_f32_e32 v158, v240, v158
	v_add_f32_e32 v159, v244, v159
	v_add_f32_e32 v160, v248, v160
	v_add_f32_e32 v161, v252, v161
	v_add_f32_e32 v158, v241, v158
	v_add_f32_e32 v159, v245, v159
	v_add_f32_e32 v160, v249, v160
	v_add_f32_e32 v161, v253, v161
	v_add_f32_dpp v158, v158, v158 row_ror:8 row_mask:0xf bank_mask:0xf bound_ctrl:1
	v_add_f32_dpp v159, v159, v159 row_ror:8 row_mask:0xf bank_mask:0xf bound_ctrl:1
	v_add_f32_dpp v160, v160, v160 row_ror:8 row_mask:0xf bank_mask:0xf bound_ctrl:1
	v_add_f32_dpp v161, v161, v161 row_ror:8 row_mask:0xf bank_mask:0xf bound_ctrl:1
	v_add_f32_dpp v158, v158, v158 row_ror:4 row_mask:0xf bank_mask:0xf bound_ctrl:1
	v_add_f32_dpp v159, v159, v159 row_ror:4 row_mask:0xf bank_mask:0xf bound_ctrl:1
	v_add_f32_dpp v160, v160, v160 row_ror:4 row_mask:0xf bank_mask:0xf bound_ctrl:1
	v_add_f32_dpp v161, v161, v161 row_ror:4 row_mask:0xf bank_mask:0xf bound_ctrl:1
	v_add_f32_dpp v158, v158, v158 row_ror:2 row_mask:0xf bank_mask:0xf bound_ctrl:1
	v_add_f32_dpp v159, v159, v159 row_ror:2 row_mask:0xf bank_mask:0xf bound_ctrl:1
	v_add_f32_dpp v160, v160, v160 row_ror:2 row_mask:0xf bank_mask:0xf bound_ctrl:1
	v_add_f32_dpp v161, v161, v161 row_ror:2 row_mask:0xf bank_mask:0xf bound_ctrl:1
	v_add_f32_dpp v158, v158, v158 row_ror:1 row_mask:0xf bank_mask:0xf bound_ctrl:1
	v_add_f32_dpp v159, v159, v159 row_ror:1 row_mask:0xf bank_mask:0xf bound_ctrl:1
	v_add_f32_dpp v160, v160, v160 row_ror:1 row_mask:0xf bank_mask:0xf bound_ctrl:1
	v_add_f32_dpp v161, v161, v161 row_ror:1 row_mask:0xf bank_mask:0xf bound_ctrl:1
; __device__ __forceinline__ float row16_sum(float v) { DPP_ADD(v, 0x128); DPP_ADD(v, 0x124); DPP_ADD(v, 0x122); DPP_ADD(v, 0x121); return v; }
; template <int EPI, int N, int K>
; __device__ __forceinline__ void gemm_phase(const bf16_t* __restrict__ A, const bf16_t* __restrict__ Bt, const EpiArgs ea) {
;     ...
; #pragma unroll
;       for (int ai = 0; ai < 2; ++ai)
; #pragma unroll
;         for (int m = 0; m < 4; ++m)
; #pragma unroll
;           for (int j = 0; j < 4; ++j) {
;             const int row = brow + ai * 128 + wr * 64 + m * 16 + fq * 4 + j;
;             const u32x2 x2 = *(const u32x2*)(ea.outb + (size_t)row * DM + c0);
;             float4 xn;
;             xn.x = __builtin_bit_cast(float, x2[0] << 16) + acc[ai][0][m][0][j]; xn.y = __builtin_bit_cast(float, x2[0] & 0xffff0000u) + acc[ai][0][m][1][j];
;             xn.z = __builtin_bit_cast(float, x2[1] << 16) + acc[ai][1][m][0][j]; xn.w = __builtin_bit_cast(float, x2[1] & 0xffff0000u) + acc[ai][1][m][1][j];
;             u32x2 o = {pk2(xn.x, xn.y), pk2(xn.z, xn.w)};
;             st_wt(ea.outb + (size_t)row * DM + c0, o);
;             float ss = xn.x * xn.x + xn.y * xn.y + xn.z * xn.z + xn.w * xn.w;
;             ss = row16_sum(ss);
;             if (fr == 0) __hip_atomic_fetch_add(ea.rowsq_out + row, (rsq_t)(ss * RSQ_SCALE), __ATOMIC_RELAXED, __HIP_MEMORY_SCOPE_AGENT);
;           }
	v_mov_b32_e32 v254, v158
	v_mov_b32_dpp v254, v159 quad_perm:[0,1,2,3] row_mask:0xf bank_mask:0x2
	v_mov_b32_dpp v254, v160 quad_perm:[0,1,2,3] row_mask:0xf bank_mask:0x4
	v_mov_b32_dpp v254, v161 quad_perm:[0,1,2,3] row_mask:0xf bank_mask:0x8
	v_mul_f32_e32 v254, 0x49800000, v254
	v_trunc_f32_e32 v254, v254
	v_mul_f32_e32 v255, 0x2f800000, v254
	v_floor_f32_e32 v255, v255
	v_fmac_f32_e32 v254, 0xcf800000, v255
	v_cvt_u32_f32_e32 v68, v254
	v_cvt_u32_f32_e32 v69, v255
	v_lshlrev_b32_e32 v238, 16, v194
	v_and_b32_e32 v239, 0xffff0000, v194
	v_lshlrev_b32_e32 v240, 16, v195
	v_and_b32_e32 v241, 0xffff0000, v195
	v_lshlrev_b32_e32 v242, 16, v196
	v_and_b32_e32 v243, 0xffff0000, v196
	v_lshlrev_b32_e32 v244, 16, v197
	v_and_b32_e32 v245, 0xffff0000, v197
	v_lshlrev_b32_e32 v246, 16, v198
	v_and_b32_e32 v247, 0xffff0000, v198
	v_lshlrev_b32_e32 v248, 16, v199
	v_and_b32_e32 v249, 0xffff0000, v199
	v_lshlrev_b32_e32 v250, 16, v200
	v_and_b32_e32 v251, 0xffff0000, v200
	v_lshlrev_b32_e32 v252, 16, v201
	v_and_b32_e32 v253, 0xffff0000, v201
	v_add_f32_e32 v238, v52, v238
	v_add_f32_e32 v239, v48, v239
	v_add_f32_e32 v240, v60, v240
	v_add_f32_e32 v241, v56, v241
	v_add_f32_e32 v242, v53, v242
	v_add_f32_e32 v243, v49, v243
	v_add_f32_e32 v244, v61, v244
	v_add_f32_e32 v245, v57, v245
	v_add_f32_e32 v246, v54, v246
	v_add_f32_e32 v247, v50, v247
	v_add_f32_e32 v248, v62, v248
	v_add_f32_e32 v249, v58, v249
	v_add_f32_e32 v250, v55, v250
	v_add_f32_e32 v251, v51, v251
	v_add_f32_e32 v252, v63, v252
	v_add_f32_e32 v253, v59, v253
	v_cvt_pk_bf16_f32 v132, v238, v239
	v_cvt_pk_bf16_f32 v133, v240, v241
	v_cvt_pk_bf16_f32 v134, v242, v243
	v_cvt_pk_bf16_f32 v135, v244, v245
	v_cvt_pk_bf16_f32 v136, v246, v247
	v_cvt_pk_bf16_f32 v137, v248, v249
	v_cvt_pk_bf16_f32 v156, v250, v251
	v_cvt_pk_bf16_f32 v157, v252, v253
	v_add_u32_e32 v228, 0x80000, v226
	global_store_dwordx2 v228, v[132:133], s[2:3] sc1
	v_add_u32_e32 v227, 0x81000, v226
	global_store_dwordx2 v227, v[134:135], s[2:3] sc1
	v_add_u32_e32 v228, 0x82000, v226
	global_store_dwordx2 v228, v[136:137], s[2:3] sc1
	v_add_u32_e32 v227, 0x83000, v226
	global_store_dwordx2 v227, v[156:157], s[2:3] sc1
	v_pk_mul_f32 v[238:239], v[238:239], v[238:239]
	v_pk_mul_f32 v[240:241], v[240:241], v[240:241]
	v_pk_mul_f32 v[242:243], v[242:243], v[242:243]
	v_pk_mul_f32 v[244:245], v[244:245], v[244:245]
	v_pk_mul_f32 v[246:247], v[246:247], v[246:247]
	v_pk_mul_f32 v[248:249], v[248:249], v[248:249]
	v_pk_mul_f32 v[250:251], v[250:251], v[250:251]
	v_pk_mul_f32 v[252:253], v[252:253], v[252:253]
	v_add_f32_e32 v158, v238, v239
	v_add_f32_e32 v159, v242, v243
	v_add_f32_e32 v160, v246, v247
	v_add_f32_e32 v161, v250, v251
	v_add_f32_e32 v158, v240, v158
	v_add_f32_e32 v159, v244, v159
	v_add_f32_e32 v160, v248, v160
	v_add_f32_e32 v161, v252, v161
	v_add_f32_e32 v158, v241, v158
	v_add_f32_e32 v159, v245, v159
	v_add_f32_e32 v160, v249, v160
	v_add_f32_e32 v161, v253, v161
	v_add_f32_dpp v158, v158, v158 row_ror:8 row_mask:0xf bank_mask:0xf bound_ctrl:1
	v_add_f32_dpp v159, v159, v159 row_ror:8 row_mask:0xf bank_mask:0xf bound_ctrl:1
	v_add_f32_dpp v160, v160, v160 row_ror:8 row_mask:0xf bank_mask:0xf bound_ctrl:1
	v_add_f32_dpp v161, v161, v161 row_ror:8 row_mask:0xf bank_mask:0xf bound_ctrl:1
	v_add_f32_dpp v158, v158, v158 row_ror:4 row_mask:0xf bank_mask:0xf bound_ctrl:1
	v_add_f32_dpp v159, v159, v159 row_ror:4 row_mask:0xf bank_mask:0xf bound_ctrl:1
	v_add_f32_dpp v160, v160, v160 row_ror:4 row_mask:0xf bank_mask:0xf bound_ctrl:1
	v_add_f32_dpp v161, v161, v161 row_ror:4 row_mask:0xf bank_mask:0xf bound_ctrl:1
	v_add_f32_dpp v158, v158, v158 row_ror:2 row_mask:0xf bank_mask:0xf bound_ctrl:1
	v_add_f32_dpp v159, v159, v159 row_ror:2 row_mask:0xf bank_mask:0xf bound_ctrl:1
	v_add_f32_dpp v160, v160, v160 row_ror:2 row_mask:0xf bank_mask:0xf bound_ctrl:1
	v_add_f32_dpp v161, v161, v161 row_ror:2 row_mask:0xf bank_mask:0xf bound_ctrl:1
	v_add_f32_dpp v158, v158, v158 row_ror:1 row_mask:0xf bank_mask:0xf bound_ctrl:1
	v_add_f32_dpp v159, v159, v159 row_ror:1 row_mask:0xf bank_mask:0xf bound_ctrl:1
	v_add_f32_dpp v160, v160, v160 row_ror:1 row_mask:0xf bank_mask:0xf bound_ctrl:1
	v_add_f32_dpp v161, v161, v161 row_ror:1 row_mask:0xf bank_mask:0xf bound_ctrl:1
	v_mov_b32_e32 v254, v158
	v_mov_b32_dpp v254, v159 quad_perm:[0,1,2,3] row_mask:0xf bank_mask:0x2
	v_mov_b32_dpp v254, v160 quad_perm:[0,1,2,3] row_mask:0xf bank_mask:0x4
	v_mov_b32_dpp v254, v161 quad_perm:[0,1,2,3] row_mask:0xf bank_mask:0x8
	v_mul_f32_e32 v254, 0x49800000, v254
	v_trunc_f32_e32 v254, v254
	v_mul_f32_e32 v255, 0x2f800000, v254
	v_floor_f32_e32 v255, v255
	v_fmac_f32_e32 v254, 0xcf800000, v255
	v_cvt_u32_f32_e32 v52, v254
	v_cvt_u32_f32_e32 v53, v255
	v_lshlrev_b32_e32 v238, 16, v202
	v_and_b32_e32 v239, 0xffff0000, v202
	v_lshlrev_b32_e32 v240, 16, v203
	v_and_b32_e32 v241, 0xffff0000, v203
	v_lshlrev_b32_e32 v242, 16, v204
	v_and_b32_e32 v243, 0xffff0000, v204
	v_lshlrev_b32_e32 v244, 16, v205
	v_and_b32_e32 v245, 0xffff0000, v205
	v_lshlrev_b32_e32 v246, 16, v206
	v_and_b32_e32 v247, 0xffff0000, v206
	v_lshlrev_b32_e32 v248, 16, v207
	v_and_b32_e32 v249, 0xffff0000, v207
	v_lshlrev_b32_e32 v250, 16, v208
	v_and_b32_e32 v251, 0xffff0000, v208
	v_lshlrev_b32_e32 v252, 16, v209
	v_and_b32_e32 v253, 0xffff0000, v209
	v_add_f32_e32 v238, v36, v238
	v_add_f32_e32 v239, v32, v239
	v_add_f32_e32 v240, v44, v240
	v_add_f32_e32 v241, v40, v241
	v_add_f32_e32 v242, v37, v242
	v_add_f32_e32 v243, v33, v243
	v_add_f32_e32 v244, v45, v244
	v_add_f32_e32 v245, v41, v245
	v_add_f32_e32 v246, v38, v246
	v_add_f32_e32 v247, v34, v247
; __device__ __forceinline__ float row16_sum(float v) { DPP_ADD(v, 0x128); DPP_ADD(v, 0x124); DPP_ADD(v, 0x122); DPP_ADD(v, 0x121); return v; }
; template <int EPI, int N, int K>
; __device__ __forceinline__ void gemm_phase(const bf16_t* __restrict__ A, const bf16_t* __restrict__ Bt, const EpiArgs ea) {
;     ...
; #pragma unroll
;       for (int ai = 0; ai < 2; ++ai)
; #pragma unroll
;         for (int m = 0; m < 4; ++m)
; #pragma unroll
;           for (int j = 0; j < 4; ++j) {
;             const int row = brow + ai * 128 + wr * 64 + m * 16 + fq * 4 + j;
;             const u32x2 x2 = *(const u32x2*)(ea.outb + (size_t)row * DM + c0);
;             float4 xn;
;             xn.x = __builtin_bit_cast(float, x2[0] << 16) + acc[ai][0][m][0][j]; xn.y = __builtin_bit_cast(float, x2[0] & 0xffff0000u) + acc[ai][0][m][1][j];
;             xn.z = __builtin_bit_cast(float, x2[1] << 16) + acc[ai][1][m][0][j]; xn.w = __builtin_bit_cast(float, x2[1] & 0xffff0000u) + acc[ai][1][m][1][j];
;             u32x2 o = {pk2(xn.x, xn.y), pk2(xn.z, xn.w)};
;             st_wt(ea.outb + (size_t)row * DM + c0, o);
;             float ss = xn.x * xn.x + xn.y * xn.y + xn.z * xn.z + xn.w * xn.w;
;             ss = row16_sum(ss);
;             if (fr == 0) __hip_atomic_fetch_add(ea.rowsq_out + row, (rsq_t)(ss * RSQ_SCALE), __ATOMIC_RELAXED, __HIP_MEMORY_SCOPE_AGENT);
;           }
	v_add_f32_e32 v248, v46, v248
	v_add_f32_e32 v249, v42, v249
	v_add_f32_e32 v250, v39, v250
	v_add_f32_e32 v251, v35, v251
	v_add_f32_e32 v252, v47, v252
	v_add_f32_e32 v253, v43, v253
	v_cvt_pk_bf16_f32 v132, v238, v239
	v_cvt_pk_bf16_f32 v133, v240, v241
	v_cvt_pk_bf16_f32 v134, v242, v243
	v_cvt_pk_bf16_f32 v135, v244, v245
	v_cvt_pk_bf16_f32 v136, v246, v247
	v_cvt_pk_bf16_f32 v137, v248, v249
	v_cvt_pk_bf16_f32 v156, v250, v251
	v_cvt_pk_bf16_f32 v157, v252, v253
	v_add_u32_e32 v228, 0x90000, v226
	global_store_dwordx2 v228, v[132:133], s[2:3] sc1
	v_add_u32_e32 v227, 0x91000, v226
	global_store_dwordx2 v227, v[134:135], s[2:3] sc1
	v_add_u32_e32 v228, 0x92000, v226
	global_store_dwordx2 v228, v[136:137], s[2:3] sc1
	v_add_u32_e32 v227, 0x93000, v226
	global_store_dwordx2 v227, v[156:157], s[2:3] sc1
	v_pk_mul_f32 v[238:239], v[238:239], v[238:239]
	v_pk_mul_f32 v[240:241], v[240:241], v[240:241]
	v_pk_mul_f32 v[242:243], v[242:243], v[242:243]
	v_pk_mul_f32 v[244:245], v[244:245], v[244:245]
	v_pk_mul_f32 v[246:247], v[246:247], v[246:247]
	v_pk_mul_f32 v[248:249], v[248:249], v[248:249]
	v_pk_mul_f32 v[250:251], v[250:251], v[250:251]
	v_pk_mul_f32 v[252:253], v[252:253], v[252:253]
	v_add_f32_e32 v158, v238, v239
	v_add_f32_e32 v159, v242, v243
	v_add_f32_e32 v160, v246, v247
	v_add_f32_e32 v161, v250, v251
	v_add_f32_e32 v158, v240, v158
	v_add_f32_e32 v159, v244, v159
	v_add_f32_e32 v160, v248, v160
	v_add_f32_e32 v161, v252, v161
	v_add_f32_e32 v158, v241, v158
	v_add_f32_e32 v159, v245, v159
	v_add_f32_e32 v160, v249, v160
	v_add_f32_e32 v161, v253, v161
	v_add_f32_dpp v158, v158, v158 row_ror:8 row_mask:0xf bank_mask:0xf bound_ctrl:1
	v_add_f32_dpp v159, v159, v159 row_ror:8 row_mask:0xf bank_mask:0xf bound_ctrl:1
	v_add_f32_dpp v160, v160, v160 row_ror:8 row_mask:0xf bank_mask:0xf bound_ctrl:1
	v_add_f32_dpp v161, v161, v161 row_ror:8 row_mask:0xf bank_mask:0xf bound_ctrl:1
	v_add_f32_dpp v158, v158, v158 row_ror:4 row_mask:0xf bank_mask:0xf bound_ctrl:1
	v_add_f32_dpp v159, v159, v159 row_ror:4 row_mask:0xf bank_mask:0xf bound_ctrl:1
	v_add_f32_dpp v160, v160, v160 row_ror:4 row_mask:0xf bank_mask:0xf bound_ctrl:1
	v_add_f32_dpp v161, v161, v161 row_ror:4 row_mask:0xf bank_mask:0xf bound_ctrl:1
	v_add_f32_dpp v158, v158, v158 row_ror:2 row_mask:0xf bank_mask:0xf bound_ctrl:1
	v_add_f32_dpp v159, v159, v159 row_ror:2 row_mask:0xf bank_mask:0xf bound_ctrl:1
	v_add_f32_dpp v160, v160, v160 row_ror:2 row_mask:0xf bank_mask:0xf bound_ctrl:1
	v_add_f32_dpp v161, v161, v161 row_ror:2 row_mask:0xf bank_mask:0xf bound_ctrl:1
	v_add_f32_dpp v158, v158, v158 row_ror:1 row_mask:0xf bank_mask:0xf bound_ctrl:1
	v_add_f32_dpp v159, v159, v159 row_ror:1 row_mask:0xf bank_mask:0xf bound_ctrl:1
	v_add_f32_dpp v160, v160, v160 row_ror:1 row_mask:0xf bank_mask:0xf bound_ctrl:1
	v_add_f32_dpp v161, v161, v161 row_ror:1 row_mask:0xf bank_mask:0xf bound_ctrl:1
	v_mov_b32_e32 v254, v158
	v_mov_b32_dpp v254, v159 quad_perm:[0,1,2,3] row_mask:0xf bank_mask:0x2
	v_mov_b32_dpp v254, v160 quad_perm:[0,1,2,3] row_mask:0xf bank_mask:0x4
	v_mov_b32_dpp v254, v161 quad_perm:[0,1,2,3] row_mask:0xf bank_mask:0x8
	v_mul_f32_e32 v254, 0x49800000, v254
	v_trunc_f32_e32 v254, v254
	v_mul_f32_e32 v255, 0x2f800000, v254
	v_floor_f32_e32 v255, v255
	v_fmac_f32_e32 v254, 0xcf800000, v255
	v_cvt_u32_f32_e32 v36, v254
	v_cvt_u32_f32_e32 v37, v255
	v_lshlrev_b32_e32 v238, 16, v210
	v_and_b32_e32 v239, 0xffff0000, v210
	v_lshlrev_b32_e32 v240, 16, v211
	v_and_b32_e32 v241, 0xffff0000, v211
	v_lshlrev_b32_e32 v242, 16, v212
	v_and_b32_e32 v243, 0xffff0000, v212
	v_lshlrev_b32_e32 v244, 16, v213
	v_and_b32_e32 v245, 0xffff0000, v213
	v_lshlrev_b32_e32 v246, 16, v214
	v_and_b32_e32 v247, 0xffff0000, v214
	v_lshlrev_b32_e32 v248, 16, v215
	v_and_b32_e32 v249, 0xffff0000, v215
	v_lshlrev_b32_e32 v250, 16, v216
	v_and_b32_e32 v251, 0xffff0000, v216
	v_lshlrev_b32_e32 v252, 16, v217
	v_and_b32_e32 v253, 0xffff0000, v217
	v_add_f32_e32 v238, v20, v238
	v_add_f32_e32 v239, v16, v239
	v_add_f32_e32 v240, v28, v240
	v_add_f32_e32 v241, v24, v241
	v_add_f32_e32 v242, v21, v242
	v_add_f32_e32 v243, v17, v243
	v_add_f32_e32 v244, v29, v244
	v_add_f32_e32 v245, v25, v245
	v_add_f32_e32 v246, v22, v246
	v_add_f32_e32 v247, v18, v247
	v_add_f32_e32 v248, v30, v248
	v_add_f32_e32 v249, v26, v249
	v_add_f32_e32 v250, v23, v250
	v_add_f32_e32 v251, v19, v251
	v_add_f32_e32 v252, v31, v252
	v_add_f32_e32 v253, v27, v253
	v_cvt_pk_bf16_f32 v132, v238, v239
	v_cvt_pk_bf16_f32 v133, v240, v241
	v_cvt_pk_bf16_f32 v134, v242, v243
	v_cvt_pk_bf16_f32 v135, v244, v245
	v_cvt_pk_bf16_f32 v136, v246, v247
	v_cvt_pk_bf16_f32 v137, v248, v249
	v_cvt_pk_bf16_f32 v156, v250, v251
	v_cvt_pk_bf16_f32 v157, v252, v253
	v_add_u32_e32 v228, 0xa0000, v226
	global_store_dwordx2 v228, v[132:133], s[2:3] sc1
	v_add_u32_e32 v227, 0xa1000, v226
	global_store_dwordx2 v227, v[134:135], s[2:3] sc1
	v_add_u32_e32 v228, 0xa2000, v226
	global_store_dwordx2 v228, v[136:137], s[2:3] sc1
	v_add_u32_e32 v227, 0xa3000, v226
	global_store_dwordx2 v227, v[156:157], s[2:3] sc1
	v_pk_mul_f32 v[238:239], v[238:239], v[238:239]
	v_pk_mul_f32 v[240:241], v[240:241], v[240:241]
	v_pk_mul_f32 v[242:243], v[242:243], v[242:243]
	v_pk_mul_f32 v[244:245], v[244:245], v[244:245]
	v_pk_mul_f32 v[246:247], v[246:247], v[246:247]
	v_pk_mul_f32 v[248:249], v[248:249], v[248:249]
	v_pk_mul_f32 v[250:251], v[250:251], v[250:251]
	v_pk_mul_f32 v[252:253], v[252:253], v[252:253]
	v_add_f32_e32 v158, v238, v239
	v_add_f32_e32 v159, v242, v243
	v_add_f32_e32 v160, v246, v247
	v_add_f32_e32 v161, v250, v251
	v_add_f32_e32 v158, v240, v158
; __device__ __forceinline__ float row16_sum(float v) { DPP_ADD(v, 0x128); DPP_ADD(v, 0x124); DPP_ADD(v, 0x122); DPP_ADD(v, 0x121); return v; }
; template <int EPI, int N, int K>
; __device__ __forceinline__ void gemm_phase(const bf16_t* __restrict__ A, const bf16_t* __restrict__ Bt, const EpiArgs ea) {
;     ...
; #pragma unroll
;       for (int ai = 0; ai < 2; ++ai)
; #pragma unroll
;         for (int m = 0; m < 4; ++m)
; #pragma unroll
;           for (int j = 0; j < 4; ++j) {
;             const int row = brow + ai * 128 + wr * 64 + m * 16 + fq * 4 + j;
;             const u32x2 x2 = *(const u32x2*)(ea.outb + (size_t)row * DM + c0);
;             float4 xn;
;             xn.x = __builtin_bit_cast(float, x2[0] << 16) + acc[ai][0][m][0][j]; xn.y = __builtin_bit_cast(float, x2[0] & 0xffff0000u) + acc[ai][0][m][1][j];
;             xn.z = __builtin_bit_cast(float, x2[1] << 16) + acc[ai][1][m][0][j]; xn.w = __builtin_bit_cast(float, x2[1] & 0xffff0000u) + acc[ai][1][m][1][j];
;             u32x2 o = {pk2(xn.x, xn.y), pk2(xn.z, xn.w)};
;             st_wt(ea.outb + (size_t)row * DM + c0, o);
;             float ss = xn.x * xn.x + xn.y * xn.y + xn.z * xn.z + xn.w * xn.w;
;             ss = row16_sum(ss);
;             if (fr == 0) __hip_atomic_fetch_add(ea.rowsq_out + row, (rsq_t)(ss * RSQ_SCALE), __ATOMIC_RELAXED, __HIP_MEMORY_SCOPE_AGENT);
;           }
	v_add_f32_e32 v159, v244, v159
	v_add_f32_e32 v160, v248, v160
	v_add_f32_e32 v161, v252, v161
	v_add_f32_e32 v158, v241, v158
	v_add_f32_e32 v159, v245, v159
	v_add_f32_e32 v160, v249, v160
	v_add_f32_e32 v161, v253, v161
	v_add_f32_dpp v158, v158, v158 row_ror:8 row_mask:0xf bank_mask:0xf bound_ctrl:1
	v_add_f32_dpp v159, v159, v159 row_ror:8 row_mask:0xf bank_mask:0xf bound_ctrl:1
	v_add_f32_dpp v160, v160, v160 row_ror:8 row_mask:0xf bank_mask:0xf bound_ctrl:1
	v_add_f32_dpp v161, v161, v161 row_ror:8 row_mask:0xf bank_mask:0xf bound_ctrl:1
	v_add_f32_dpp v158, v158, v158 row_ror:4 row_mask:0xf bank_mask:0xf bound_ctrl:1
	v_add_f32_dpp v159, v159, v159 row_ror:4 row_mask:0xf bank_mask:0xf bound_ctrl:1
	v_add_f32_dpp v160, v160, v160 row_ror:4 row_mask:0xf bank_mask:0xf bound_ctrl:1
	v_add_f32_dpp v161, v161, v161 row_ror:4 row_mask:0xf bank_mask:0xf bound_ctrl:1
	v_add_f32_dpp v158, v158, v158 row_ror:2 row_mask:0xf bank_mask:0xf bound_ctrl:1
	v_add_f32_dpp v159, v159, v159 row_ror:2 row_mask:0xf bank_mask:0xf bound_ctrl:1
	v_add_f32_dpp v160, v160, v160 row_ror:2 row_mask:0xf bank_mask:0xf bound_ctrl:1
	v_add_f32_dpp v161, v161, v161 row_ror:2 row_mask:0xf bank_mask:0xf bound_ctrl:1
	v_add_f32_dpp v158, v158, v158 row_ror:1 row_mask:0xf bank_mask:0xf bound_ctrl:1
	v_add_f32_dpp v159, v159, v159 row_ror:1 row_mask:0xf bank_mask:0xf bound_ctrl:1
	v_add_f32_dpp v160, v160, v160 row_ror:1 row_mask:0xf bank_mask:0xf bound_ctrl:1
	v_add_f32_dpp v161, v161, v161 row_ror:1 row_mask:0xf bank_mask:0xf bound_ctrl:1
	v_mov_b32_e32 v254, v158
	v_mov_b32_dpp v254, v159 quad_perm:[0,1,2,3] row_mask:0xf bank_mask:0x2
	v_mov_b32_dpp v254, v160 quad_perm:[0,1,2,3] row_mask:0xf bank_mask:0x4
	v_mov_b32_dpp v254, v161 quad_perm:[0,1,2,3] row_mask:0xf bank_mask:0x8
	v_mul_f32_e32 v254, 0x49800000, v254
	v_trunc_f32_e32 v254, v254
	v_mul_f32_e32 v255, 0x2f800000, v254
	v_floor_f32_e32 v255, v255
	v_fmac_f32_e32 v254, 0xcf800000, v255
	v_cvt_u32_f32_e32 v20, v254
	v_cvt_u32_f32_e32 v21, v255
	v_lshlrev_b32_e32 v238, 16, v218
	v_and_b32_e32 v239, 0xffff0000, v218
	v_lshlrev_b32_e32 v240, 16, v219
	v_and_b32_e32 v241, 0xffff0000, v219
	v_lshlrev_b32_e32 v242, 16, v220
	v_and_b32_e32 v243, 0xffff0000, v220
	v_lshlrev_b32_e32 v244, 16, v221
	v_and_b32_e32 v245, 0xffff0000, v221
	v_lshlrev_b32_e32 v246, 16, v222
	v_and_b32_e32 v247, 0xffff0000, v222
	v_lshlrev_b32_e32 v248, 16, v223
	v_and_b32_e32 v249, 0xffff0000, v223
	v_lshlrev_b32_e32 v250, 16, v224
	v_and_b32_e32 v251, 0xffff0000, v224
	v_lshlrev_b32_e32 v252, 16, v225
	v_and_b32_e32 v253, 0xffff0000, v225
	v_add_f32_e32 v238, v8, v238
	v_add_f32_e32 v239, v12, v239
	v_add_f32_e32 v240, v4, v240
	v_add_f32_e32 v241, v0, v241
	v_add_f32_e32 v242, v9, v242
	v_add_f32_e32 v243, v13, v243
	v_add_f32_e32 v244, v5, v244
	v_add_f32_e32 v245, v1, v245
	v_add_f32_e32 v246, v10, v246
	v_add_f32_e32 v247, v14, v247
	v_add_f32_e32 v248, v6, v248
	v_add_f32_e32 v249, v2, v249
	v_add_f32_e32 v250, v11, v250
	v_add_f32_e32 v251, v15, v251
	v_add_f32_e32 v252, v7, v252
	v_add_f32_e32 v253, v3, v253
	v_cvt_pk_bf16_f32 v132, v238, v239
	v_cvt_pk_bf16_f32 v133, v240, v241
	v_cvt_pk_bf16_f32 v134, v242, v243
	v_cvt_pk_bf16_f32 v135, v244, v245
	v_cvt_pk_bf16_f32 v136, v246, v247
	v_cvt_pk_bf16_f32 v137, v248, v249
	v_cvt_pk_bf16_f32 v156, v250, v251
	v_cvt_pk_bf16_f32 v157, v252, v253
	v_add_u32_e32 v228, 0xb0000, v226
	global_store_dwordx2 v228, v[132:133], s[2:3] sc1
	v_add_u32_e32 v227, 0xb1000, v226
	global_store_dwordx2 v227, v[134:135], s[2:3] sc1
	v_add_u32_e32 v228, 0xb2000, v226
	global_store_dwordx2 v228, v[136:137], s[2:3] sc1
	v_add_u32_e32 v227, 0xb3000, v226
	global_store_dwordx2 v227, v[156:157], s[2:3] sc1
	v_pk_mul_f32 v[238:239], v[238:239], v[238:239]
	v_pk_mul_f32 v[240:241], v[240:241], v[240:241]
	v_pk_mul_f32 v[242:243], v[242:243], v[242:243]
	v_pk_mul_f32 v[244:245], v[244:245], v[244:245]
; __device__ __forceinline__ float row16_sum(float v) { DPP_ADD(v, 0x128); DPP_ADD(v, 0x124); DPP_ADD(v, 0x122); DPP_ADD(v, 0x121); return v; }
; template <int EPI, int N, int K>
; __device__ __forceinline__ void gemm_phase(const bf16_t* __restrict__ A, const bf16_t* __restrict__ Bt, const EpiArgs ea) {
;     ...
; #pragma unroll
;       for (int ai = 0; ai < 2; ++ai)
; #pragma unroll
;         for (int m = 0; m < 4; ++m)
; #pragma unroll
;           for (int j = 0; j < 4; ++j) {
;             const int row = brow + ai * 128 + wr * 64 + m * 16 + fq * 4 + j;
;             const u32x2 x2 = *(const u32x2*)(ea.outb + (size_t)row * DM + c0);
;             float4 xn;
;             xn.x = __builtin_bit_cast(float, x2[0] << 16) + acc[ai][0][m][0][j]; xn.y = __builtin_bit_cast(float, x2[0] & 0xffff0000u) + acc[ai][0][m][1][j];
;             xn.z = __builtin_bit_cast(float, x2[1] << 16) + acc[ai][1][m][0][j]; xn.w = __builtin_bit_cast(float, x2[1] & 0xffff0000u) + acc[ai][1][m][1][j];
;             u32x2 o = {pk2(xn.x, xn.y), pk2(xn.z, xn.w)};
;             st_wt(ea.outb + (size_t)row * DM + c0, o);
;             float ss = xn.x * xn.x + xn.y * xn.y + xn.z * xn.z + xn.w * xn.w;
;             ss = row16_sum(ss);
;             if (fr == 0) __hip_atomic_fetch_add(ea.rowsq_out + row, (rsq_t)(ss * RSQ_SCALE), __ATOMIC_RELAXED, __HIP_MEMORY_SCOPE_AGENT);
;           }
	v_pk_mul_f32 v[246:247], v[246:247], v[246:247]
	v_pk_mul_f32 v[248:249], v[248:249], v[248:249]
	v_pk_mul_f32 v[250:251], v[250:251], v[250:251]
	v_pk_mul_f32 v[252:253], v[252:253], v[252:253]
	v_add_f32_e32 v158, v238, v239
	v_add_f32_e32 v159, v242, v243
	v_add_f32_e32 v160, v246, v247
	v_add_f32_e32 v161, v250, v251
	v_add_f32_e32 v158, v240, v158
	v_add_f32_e32 v159, v244, v159
	v_add_f32_e32 v160, v248, v160
	v_add_f32_e32 v161, v252, v161
	v_add_f32_e32 v158, v241, v158
	v_add_f32_e32 v159, v245, v159
	v_add_f32_e32 v160, v249, v160
	v_add_f32_e32 v161, v253, v161
	v_add_f32_dpp v158, v158, v158 row_ror:8 row_mask:0xf bank_mask:0xf bound_ctrl:1
	v_add_f32_dpp v159, v159, v159 row_ror:8 row_mask:0xf bank_mask:0xf bound_ctrl:1
	v_add_f32_dpp v160, v160, v160 row_ror:8 row_mask:0xf bank_mask:0xf bound_ctrl:1
	v_add_f32_dpp v161, v161, v161 row_ror:8 row_mask:0xf bank_mask:0xf bound_ctrl:1
	v_add_f32_dpp v158, v158, v158 row_ror:4 row_mask:0xf bank_mask:0xf bound_ctrl:1
	v_add_f32_dpp v159, v159, v159 row_ror:4 row_mask:0xf bank_mask:0xf bound_ctrl:1
	v_add_f32_dpp v160, v160, v160 row_ror:4 row_mask:0xf bank_mask:0xf bound_ctrl:1
	v_add_f32_dpp v161, v161, v161 row_ror:4 row_mask:0xf bank_mask:0xf bound_ctrl:1
	v_add_f32_dpp v158, v158, v158 row_ror:2 row_mask:0xf bank_mask:0xf bound_ctrl:1
	v_add_f32_dpp v159, v159, v159 row_ror:2 row_mask:0xf bank_mask:0xf bound_ctrl:1
	v_add_f32_dpp v160, v160, v160 row_ror:2 row_mask:0xf bank_mask:0xf bound_ctrl:1
	v_add_f32_dpp v161, v161, v161 row_ror:2 row_mask:0xf bank_mask:0xf bound_ctrl:1
	v_add_f32_dpp v158, v158, v158 row_ror:1 row_mask:0xf bank_mask:0xf bound_ctrl:1
	v_add_f32_dpp v159, v159, v159 row_ror:1 row_mask:0xf bank_mask:0xf bound_ctrl:1
	v_add_f32_dpp v160, v160, v160 row_ror:1 row_mask:0xf bank_mask:0xf bound_ctrl:1
	v_add_f32_dpp v161, v161, v161 row_ror:1 row_mask:0xf bank_mask:0xf bound_ctrl:1
	v_mov_b32_e32 v254, v158
	v_mov_b32_dpp v254, v159 quad_perm:[0,1,2,3] row_mask:0xf bank_mask:0x2
	v_mov_b32_dpp v254, v160 quad_perm:[0,1,2,3] row_mask:0xf bank_mask:0x4
	v_mov_b32_dpp v254, v161 quad_perm:[0,1,2,3] row_mask:0xf bank_mask:0x8
	v_mul_f32_e32 v254, 0x49800000, v254
	v_trunc_f32_e32 v254, v254
	v_mul_f32_e32 v255, 0x2f800000, v254
	v_floor_f32_e32 v255, v255
	v_fmac_f32_e32 v254, 0xcf800000, v255
	v_cvt_u32_f32_e32 v8, v254
	v_cvt_u32_f32_e32 v9, v255
	v_and_b32_e32 v227, 12, v145
	v_cmp_eq_u32_e32 vcc, 0, v227
	s_and_b64 exec, exec, vcc
	ds_write_b64 v229, v[116:117]
	ds_write_b64 v229, v[100:101] offset:512
	ds_write_b64 v229, v[84:85] offset:1024
	ds_write_b64 v229, v[68:69] offset:1536
	ds_write_b64 v229, v[52:53] offset:2048
	ds_write_b64 v229, v[36:37] offset:2560
	ds_write_b64 v229, v[20:21] offset:3072
	ds_write_b64 v229, v[8:9] offset:3584
	s_mov_b64 exec, -1
	v_bfe_u32 v227, v146, 2, 2
	v_bfe_u32 v228, v145, 2, 4
	v_lshl_add_u32 v227, v227, 4, v228
	v_lshrrev_b32_e32 v228, 6, v145
	v_lshl_add_u32 v228, v228, 5, v227
	v_lshrrev_b32_e32 v230, 6, v146
	v_lshlrev_b32_e32 v231, 12, v230
	v_lshl_add_u32 v231, v228, 5, v231
	v_add_u32_e32 v231, 0x20410, v231
	v_cmp_gt_u32_e32 vcc, 32, v227
	v_lshrrev_b32_e32 v227, 6, v228
	v_lshlrev_b32_e32 v227, 7, v227
	v_and_b32_e32 v228, 63, v228
	v_add3_u32 v227, v227, v228, s29
	v_lshl_add_u32 v227, v230, 6, v227
	v_lshlrev_b32_e32 v227, 3, v227
	s_waitcnt lgkmcnt(0)
	s_barrier
	s_and_b64 exec, exec, vcc
	ds_read_b128 v[238:241], v231
	ds_read_b128 v[242:245], v231 offset:16
	s_waitcnt lgkmcnt(0)
	v_add_co_u32_e32 v246, vcc, v238, v240
	s_nop 1
	v_addc_co_u32_e32 v247, vcc, v239, v241, vcc
	v_add_co_u32_e32 v246, vcc, v246, v242
	s_nop 1
	v_addc_co_u32_e32 v247, vcc, v247, v243, vcc
	v_add_co_u32_e32 v246, vcc, v246, v244
	s_nop 1
	v_addc_co_u32_e32 v247, vcc, v247, v245, vcc
	global_atomic_add_x2 v227, v[246:247], s[0:1]
	s_mov_b64 exec, -1
	s_mov_b64 s[2:3], -1
	s_branch .LBB0_562

; __global__ void __launch_bounds__(NTHR) fwd_megakernel(Params p) {
;   cg::grid_group grid = cg::this_grid();
;   char* ws = p.ws;
;   bf16_t* xb = (bf16_t*)(ws + OFF_XB);
;   bf16_t* qkv = (bf16_t*)(ws + OFF_QKV);
;   bf16_t* att = (bf16_t*)(ws + OFF_ATT);
;   bf16_t* ub = (bf16_t*)(ws + OFF_U);
;   rsq_t* rowsq = (rsq_t*)(ws + OFF_ROWSQ);
;     ...
;   if (p.out == nullptr) grid.sync();
;   for (int r = 0; r < REP_P0; ++r) { phase0(p); xcd_barrier(xb_); }
;   for (int i = 0; i < NLAYERS; ++i) {
;     const int j = i >> 1;
;     const bf16_t* wo;
;     if ((i & 1) == 0) {
;       EpiArgs e{rowsq + (size_t)(2 * i) * TOK, qkv, nullptr, nullptr, nullptr};
;       for (int r = 0; r < REP_QKV; ++r) gemm_phase<EPI_QKV, NQA, DM>(xb, (const bf16_t*)(ws + OFF_WQKVA + j * SZ_WQKVA), e);
;       xcd_barrier(xb_);
;       for (int r = 0; r < REP_MIX; ++r) attn_a_phase(qkv, att, p.a_sinks + j * 32);
;       wo = (const bf16_t*)(ws + OFF_WOA + j * SZ_WO);
;     } else {
;       EpiArgs e{rowsq + (size_t)(2 * i) * TOK, qkv, nullptr, nullptr, nullptr};
;       for (int r = 0; r < REP_QKV; ++r) gemm_phase<EPI_QKV, NQB, DM>(xb, (const bf16_t*)(ws + OFF_WQKVB + j * SZ_WQKVB), e);
;       xcd_barrier(xb_);
;       for (int r = 0; r < REP_MIX; ++r) attn_b_phase(qkv, att);
;       wo = (const bf16_t*)(ws + OFF_WOB + j * SZ_WO);
;     }
;     xcd_barrier(xb_);
;     {
;       EpiArgs e{nullptr, xb, nullptr, nullptr, rowsq + (size_t)(2 * i + 1) * TOK};
;       gemm_phase<EPI_RES, DM, DM>(att, wo, e);
;     }
;     xcd_barrier(xb_);
;     {
;       EpiArgs e{rowsq + (size_t)(2 * i + 1) * TOK, ub, nullptr, nullptr, nullptr};
;       for (int r = 0; r < REP_MLPIN; ++r) gemm_phase<EPI_MLP, DFF, DM>(xb, (const bf16_t*)(ws + OFF_WIN + i * SZ_WFF), e);
;     }
;     xcd_barrier(xb_);
;     {
;       EpiArgs e{nullptr, xb, nullptr, nullptr, rowsq + (size_t)(2 * i + 2) * TOK};
;       gemm_phase<EPI_RES, DM, DFF>(ub, (const bf16_t*)(ws + OFF_WOUT + i * SZ_WFF), e);
;     }
;     xcd_barrier(xb_);
;   }
;   final_norm_phase(xb, rowsq + (size_t)(2 * NLAYERS) * TOK, p.final_norm, p.out);
; }
	.amdhsa_kernel _Z14fwd_megakernel6Params
		.amdhsa_group_segment_fixed_size 16
		.amdhsa_private_segment_fixed_size 0
		.amdhsa_kernarg_size 360
		.amdhsa_user_sgpr_count 2
		.amdhsa_user_sgpr_dispatch_ptr 0
		.amdhsa_user_sgpr_queue_ptr 0
		.amdhsa_user_sgpr_kernarg_segment_ptr 1
		.amdhsa_user_sgpr_dispatch_id 0
		.amdhsa_user_sgpr_kernarg_preload_length 0
		.amdhsa_user_sgpr_kernarg_preload_offset 0
		.amdhsa_user_sgpr_private_segment_size 0
		.amdhsa_uses_dynamic_stack 0
		.amdhsa_enable_private_segment 0
		.amdhsa_system_sgpr_workgroup_id_x 1
		.amdhsa_system_sgpr_workgroup_id_y 0
		.amdhsa_system_sgpr_workgroup_id_z 0
		.amdhsa_system_sgpr_workgroup_info 0
		.amdhsa_system_vgpr_workitem_id 2
		.amdhsa_next_free_vgpr 256
		.amdhsa_next_free_sgpr 100
		.amdhsa_accum_offset 256
		.amdhsa_reserve_vcc 1
		.amdhsa_float_round_mode_32 0
		.amdhsa_float_round_mode_16_64 0
		.amdhsa_float_denorm_mode_32 3
		.amdhsa_float_denorm_mode_16_64 3
		.amdhsa_dx10_clamp 1
		.amdhsa_ieee_mode 1
		.amdhsa_fp16_overflow 0
		.amdhsa_tg_split 0
		.amdhsa_exception_fp_ieee_invalid_op 0
		.amdhsa_exception_fp_denorm_src 0
		.amdhsa_exception_fp_ieee_div_zero 0
		.amdhsa_exception_fp_ieee_overflow 0
		.amdhsa_exception_fp_ieee_underflow 0
		.amdhsa_exception_fp_ieee_inexact 0
		.amdhsa_exception_int_div_zero 0
	.end_amdhsa_kernel

; __global__ void __launch_bounds__(NTHR) fwd_megakernel(Params p) {
;   cg::grid_group grid = cg::this_grid();
;   char* ws = p.ws;
;   bf16_t* xb = (bf16_t*)(ws + OFF_XB);
;   bf16_t* qkv = (bf16_t*)(ws + OFF_QKV);
;   bf16_t* att = (bf16_t*)(ws + OFF_ATT);
;   bf16_t* ub = (bf16_t*)(ws + OFF_U);
;   rsq_t* rowsq = (rsq_t*)(ws + OFF_ROWSQ);
;     ...
;   if (p.out == nullptr) grid.sync();
;   for (int r = 0; r < REP_P0; ++r) { phase0(p); xcd_barrier(xb_); }
;   for (int i = 0; i < NLAYERS; ++i) {
;     const int j = i >> 1;
;     const bf16_t* wo;
;     if ((i & 1) == 0) {
;       EpiArgs e{rowsq + (size_t)(2 * i) * TOK, qkv, nullptr, nullptr, nullptr};
;       for (int r = 0; r < REP_QKV; ++r) gemm_phase<EPI_QKV, NQA, DM>(xb, (const bf16_t*)(ws + OFF_WQKVA + j * SZ_WQKVA), e);
;       xcd_barrier(xb_);
;       for (int r = 0; r < REP_MIX; ++r) attn_a_phase(qkv, att, p.a_sinks + j * 32);
;       wo = (const bf16_t*)(ws + OFF_WOA + j * SZ_WO);
;     } else {
;       EpiArgs e{rowsq + (size_t)(2 * i) * TOK, qkv, nullptr, nullptr, nullptr};
;       for (int r = 0; r < REP_QKV; ++r) gemm_phase<EPI_QKV, NQB, DM>(xb, (const bf16_t*)(ws + OFF_WQKVB + j * SZ_WQKVB), e);
;       xcd_barrier(xb_);
;       for (int r = 0; r < REP_MIX; ++r) attn_b_phase(qkv, att);
;       wo = (const bf16_t*)(ws + OFF_WOB + j * SZ_WO);
;     }
;     xcd_barrier(xb_);
;     {
;       EpiArgs e{nullptr, xb, nullptr, nullptr, rowsq + (size_t)(2 * i + 1) * TOK};
;       gemm_phase<EPI_RES, DM, DM>(att, wo, e);
;     }
;     xcd_barrier(xb_);
;     {
;       EpiArgs e{rowsq + (size_t)(2 * i + 1) * TOK, ub, nullptr, nullptr, nullptr};
;       for (int r = 0; r < REP_MLPIN; ++r) gemm_phase<EPI_MLP, DFF, DM>(xb, (const bf16_t*)(ws + OFF_WIN + i * SZ_WFF), e);
;     }
;     xcd_barrier(xb_);
;     {
;       EpiArgs e{nullptr, xb, nullptr, nullptr, rowsq + (size_t)(2 * i + 2) * TOK};
;       gemm_phase<EPI_RES, DM, DFF>(ub, (const bf16_t*)(ws + OFF_WOUT + i * SZ_WFF), e);
;     }
;     xcd_barrier(xb_);
;   }
;   final_norm_phase(xb, rowsq + (size_t)(2 * NLAYERS) * TOK, p.final_norm, p.out);
; }
.Lfunc_end0:
	.size	_Z14fwd_megakernel6Params, .Lfunc_end0-_Z14fwd_megakernel6Params
	.set _Z14fwd_megakernel6Params.num_vgpr, 256
	.set _Z14fwd_megakernel6Params.num_agpr, 0
	.set _Z14fwd_megakernel6Params.numbered_sgpr, 100
	.set _Z14fwd_megakernel6Params.num_named_barrier, 0
	.set _Z14fwd_megakernel6Params.private_seg_size, 0
	.set _Z14fwd_megakernel6Params.uses_vcc, 1
	.set _Z14fwd_megakernel6Params.uses_flat_scratch, 0
	.set _Z14fwd_megakernel6Params.has_dyn_sized_stack, 0
	.set _Z14fwd_megakernel6Params.has_recursion, 0
	.set _Z14fwd_megakernel6Params.has_indirect_call, 0

amdhsa.kernels:
  - .agpr_count:     0
    .args:
      - .offset:         0
        .size:           104
        .value_kind:     by_value
      - .offset:         104
        .size:           4
        .value_kind:     hidden_block_count_x
      - .offset:         108
        .size:           4
        .value_kind:     hidden_block_count_y
      - .offset:         112
        .size:           4
        .value_kind:     hidden_block_count_z
      - .offset:         116
        .size:           2
        .value_kind:     hidden_group_size_x
      - .offset:         118
        .size:           2
        .value_kind:     hidden_group_size_y
      - .offset:         120
        .size:           2
        .value_kind:     hidden_group_size_z
      - .offset:         122
        .size:           2
        .value_kind:     hidden_remainder_x
      - .offset:         124
        .size:           2
        .value_kind:     hidden_remainder_y
      - .offset:         126
        .size:           2
        .value_kind:     hidden_remainder_z
      - .offset:         144
        .size:           8
        .value_kind:     hidden_global_offset_x
      - .offset:         152
        .size:           8
        .value_kind:     hidden_global_offset_y
      - .offset:         160
        .size:           8
        .value_kind:     hidden_global_offset_z
      - .offset:         168
        .size:           2
        .value_kind:     hidden_grid_dims
      - .offset:         192
        .size:           8
        .value_kind:     hidden_multigrid_sync_arg
      - .offset:         224
        .size:           4
        .value_kind:     hidden_dynamic_lds_size
    .group_segment_fixed_size: 16
    .kernarg_segment_align: 8
    .kernarg_segment_size: 360
    .language:       OpenCL C
    .language_version:
      - 2
      - 0
    .max_flat_workgroup_size: 512
    .name:           _Z14fwd_megakernel6Params
    .private_segment_fixed_size: 0
    .sgpr_count:     106
    .sgpr_spill_count: 146
    .symbol:         _Z14fwd_megakernel6Params.kd
    .uniform_work_group_size: 1
    .uses_dynamic_stack: false
    .vgpr_count:     256
    .vgpr_spill_count: 0
    .wavefront_size: 64
